# v49 + loop-edge edit: trip counter / K-offset updates and exit compare moved to the tail of phase 4's load segment; hipcc's vmcnt(0) in front of the single-unit K-loops dropped
# speedup vs baseline: 1.0088x; 1.0088x over previous
; #define PG8_WAIT_V(n) asm volatile("s_waitcnt vmcnt(" #n ")" ::: "memory")
; template <class Epi, bool ALIGN_EPI, bool SP2, class Hook>
; __device__ __forceinline__ void gemm_phase(LAS unsigned char* lds, const Gemm g, const StaticOrder& S, const Epi& E, Acc& acc, const bool fresh, const Hook& H, const int wave_id) {
;     ...
;         for (int t = t0; t < nt; t += 2) {
;             const bool last = (t == nt - 2);
;             const Src a1 = cA + (size_t)(t + 1) * kstep;
;             const Src a2 = last ? nA : cA + (size_t)(t + 2) * kstep, b2 = last ? nB : cB + (size_t)(t + 2) * kstep;
;             const Src a3 = a2 + kstep, b3 = b2 + kstep;
;             if (last && has_next) H(nxt);
;             if constexpr (SP2) {
;             PG8_TRIP_SP2(PG8_WAIT_V(8));
.LBB0_391:
	s_add_i32 s100, s56, 0xfffc0000
	v_add_u32_e32 v150, 0x10000, v148
	v_add_u32_e32 v151, 0x14000, v148
	ds_read_b128 v[132:135], v150
	ds_read_b128 v[136:139], v150 offset:1024
	ds_read_b128 v[140:143], v150 offset:2048
	ds_read_b128 v[152:155], v150 offset:3072
	ds_read_b128 v[156:159], v151
	ds_read_b128 v[160:163], v151 offset:1024
	ds_read_b128 v[164:167], v151 offset:2048
	ds_read_b128 v[168:171], v151 offset:3072
	s_mov_b32 m0, s41
	s_nop 0
	buffer_load_dwordx4 v144, s[8:11], s100 offen lds
	s_mov_b32 m0, s33
	s_nop 0
	buffer_load_dwordx4 v146, s[8:11], s100 offen lds
	s_mov_b32 m0, s45
	ds_read_b128 v[172:175], v149
	ds_read_b128 v[176:179], v149 offset:1024
	ds_read_b128 v[180:183], v149 offset:2048
	ds_read_b128 v[184:187], v149 offset:3072
	ds_read_b128 v[188:191], v149 offset:4096
	ds_read_b128 v[212:215], v149 offset:5120
	ds_read_b128 v[216:219], v149 offset:6144
	ds_read_b128 v[228:231], v149 offset:7168
	buffer_load_dwordx4 v144, s[8:11], s56 offen lds
	s_mov_b32 m0, s46
	s_nop 0
	buffer_load_dwordx4 v146, s[8:11], s56 offen lds
	s_waitcnt vmcnt(8)
	s_waitcnt lgkmcnt(0)
	s_setprio 1
	s_barrier
	v_mfma_f32_16x16x32_bf16 v[120:123], v[132:135], v[172:175], v[120:123]
	v_mfma_f32_16x16x32_bf16 v[112:115], v[140:143], v[172:175], v[112:115]
	v_mfma_f32_16x16x32_bf16 v[100:103], v[132:135], v[180:183], v[100:103]
	v_mfma_f32_16x16x32_bf16 v[88:91], v[140:143], v[180:183], v[88:91]
	v_mfma_f32_16x16x32_bf16 v[68:71], v[132:135], v[188:191], v[68:71]
	v_mfma_f32_16x16x32_bf16 v[56:59], v[140:143], v[188:191], v[56:59]
	v_mfma_f32_16x16x32_bf16 v[36:39], v[132:135], v[216:219], v[36:39]
	v_mfma_f32_16x16x32_bf16 v[28:31], v[140:143], v[216:219], v[28:31]
	v_mfma_f32_16x16x32_bf16 v[120:123], v[136:139], v[176:179], v[120:123]
	v_mfma_f32_16x16x32_bf16 v[112:115], v[152:155], v[176:179], v[112:115]
	v_mfma_f32_16x16x32_bf16 v[100:103], v[136:139], v[184:187], v[100:103]
	v_mfma_f32_16x16x32_bf16 v[88:91], v[152:155], v[184:187], v[88:91]
	v_mfma_f32_16x16x32_bf16 v[68:71], v[136:139], v[212:215], v[68:71]
	v_mfma_f32_16x16x32_bf16 v[56:59], v[152:155], v[212:215], v[56:59]
	v_mfma_f32_16x16x32_bf16 v[36:39], v[136:139], v[228:231], v[36:39]
	v_mfma_f32_16x16x32_bf16 v[28:31], v[152:155], v[228:231], v[28:31]
	v_mfma_f32_16x16x32_bf16 v[128:131], v[156:159], v[172:175], v[128:131]
	v_mfma_f32_16x16x32_bf16 v[124:127], v[164:167], v[172:175], v[124:127]
	v_mfma_f32_16x16x32_bf16 v[116:119], v[156:159], v[180:183], v[116:119]
	v_mfma_f32_16x16x32_bf16 v[108:111], v[164:167], v[180:183], v[108:111]
	v_mfma_f32_16x16x32_bf16 v[92:95], v[156:159], v[188:191], v[92:95]
	v_mfma_f32_16x16x32_bf16 v[80:83], v[164:167], v[188:191], v[80:83]
	v_mfma_f32_16x16x32_bf16 v[64:67], v[156:159], v[216:219], v[64:67]
	v_mfma_f32_16x16x32_bf16 v[48:51], v[164:167], v[216:219], v[48:51]
	v_mfma_f32_16x16x32_bf16 v[128:131], v[160:163], v[176:179], v[128:131]
	v_mfma_f32_16x16x32_bf16 v[124:127], v[168:171], v[176:179], v[124:127]
	v_mfma_f32_16x16x32_bf16 v[116:119], v[160:163], v[184:187], v[116:119]
	v_mfma_f32_16x16x32_bf16 v[108:111], v[168:171], v[184:187], v[108:111]
	v_mfma_f32_16x16x32_bf16 v[92:95], v[160:163], v[212:215], v[92:95]
	v_mfma_f32_16x16x32_bf16 v[80:83], v[168:171], v[212:215], v[80:83]
	v_mfma_f32_16x16x32_bf16 v[64:67], v[160:163], v[228:231], v[64:67]
	v_mfma_f32_16x16x32_bf16 v[48:51], v[168:171], v[228:231], v[48:51]
	s_barrier
	s_setprio 0
	s_add_i32 s12, s56, 0xfffc0080
	s_cmp_eq_u32 s29, 12
	s_cselect_b32 s60, s68, s12
	s_cselect_b32 s13, s5, s77
	s_cselect_b32 s12, s4, s76
	s_cselect_b32 s15, s7, s55
	s_cselect_b32 s14, s6, s54
	s_cselect_b32 s58, s69, s57
	s_cselect_b32 s16, s0, s8
	s_cselect_b32 s17, s1, s9
	s_cselect_b32 s18, s2, s10
	s_cselect_b32 s19, s3, s11
	s_or_b32 s59, s60, 0x80
	s_mov_b32 m0, s92
	ds_read_b128 v[172:175], v149 offset:16384
	ds_read_b128 v[176:179], v149 offset:17408
	ds_read_b128 v[180:183], v149 offset:18432
	ds_read_b128 v[184:187], v149 offset:19456
	ds_read_b128 v[188:191], v149 offset:20480
	ds_read_b128 v[212:215], v149 offset:21504
	ds_read_b128 v[216:219], v149 offset:22528
	ds_read_b128 v[228:231], v149 offset:23552
	buffer_load_dwordx4 v145, s[12:15], s58 offen lds
	s_mov_b32 m0, s93
	s_add_i32 s61, s58, 0x40000
	buffer_load_dwordx4 v147, s[12:15], s58 offen lds
	s_mov_b32 m0, s94
	s_nop 0
	buffer_load_dwordx4 v145, s[12:15], s61 offen lds
	s_mov_b32 m0, s95
	s_nop 0
	buffer_load_dwordx4 v147, s[12:15], s61 offen lds
	s_waitcnt vmcnt(6)
	s_waitcnt lgkmcnt(0)
	s_setprio 1
	s_barrier
	v_mfma_f32_16x16x32_bf16 v[72:75], v[132:135], v[172:175], v[72:75]
	v_mfma_f32_16x16x32_bf16 v[60:63], v[140:143], v[172:175], v[60:63]
	v_mfma_f32_16x16x32_bf16 v[40:43], v[132:135], v[180:183], v[40:43]
	v_mfma_f32_16x16x32_bf16 v[32:35], v[140:143], v[180:183], v[32:35]
	v_mfma_f32_16x16x32_bf16 v[16:19], v[132:135], v[188:191], v[16:19]
	v_mfma_f32_16x16x32_bf16 v[12:15], v[140:143], v[188:191], v[12:15]
	v_mfma_f32_16x16x32_bf16 v[8:11], v[132:135], v[216:219], v[8:11]
	v_mfma_f32_16x16x32_bf16 v[2:5], v[140:143], v[216:219], v[4:7]
	v_mfma_f32_16x16x32_bf16 v[72:75], v[136:139], v[176:179], v[72:75]
	v_mfma_f32_16x16x32_bf16 v[60:63], v[152:155], v[176:179], v[60:63]
	v_mfma_f32_16x16x32_bf16 v[40:43], v[136:139], v[184:187], v[40:43]
	v_mfma_f32_16x16x32_bf16 v[32:35], v[152:155], v[184:187], v[32:35]
	v_mfma_f32_16x16x32_bf16 v[16:19], v[136:139], v[212:215], v[16:19]
	v_mfma_f32_16x16x32_bf16 v[12:15], v[152:155], v[212:215], v[12:15]
	v_mfma_f32_16x16x32_bf16 v[8:11], v[136:139], v[228:231], v[8:11]
	v_mfma_f32_16x16x32_bf16 v[2:5], v[152:155], v[228:231], v[2:5]
	v_mfma_f32_16x16x32_bf16 v[96:99], v[156:159], v[172:175], v[96:99]
	v_mfma_f32_16x16x32_bf16 v[104:107], v[164:167], v[172:175], v[104:107]
	v_mfma_f32_16x16x32_bf16 v[84:87], v[156:159], v[180:183], v[84:87]
	v_mfma_f32_16x16x32_bf16 v[76:79], v[164:167], v[180:183], v[76:79]
	v_mfma_f32_16x16x32_bf16 v[52:55], v[156:159], v[188:191], v[52:55]
	v_mfma_f32_16x16x32_bf16 v[44:47], v[164:167], v[188:191], v[44:47]
	v_mfma_f32_16x16x32_bf16 v[24:27], v[156:159], v[216:219], v[24:27]
	v_mfma_f32_16x16x32_bf16 v[20:23], v[164:167], v[216:219], v[20:23]
	v_mfma_f32_16x16x32_bf16 v[96:99], v[160:163], v[176:179], v[96:99]
	v_mfma_f32_16x16x32_bf16 v[104:107], v[168:171], v[176:179], v[104:107]
	v_mfma_f32_16x16x32_bf16 v[84:87], v[160:163], v[184:187], v[84:87]
	v_mfma_f32_16x16x32_bf16 v[76:79], v[168:171], v[184:187], v[76:79]
	v_mfma_f32_16x16x32_bf16 v[52:55], v[160:163], v[212:215], v[52:55]
	v_mfma_f32_16x16x32_bf16 v[44:47], v[168:171], v[212:215], v[44:47]
	v_mfma_f32_16x16x32_bf16 v[24:27], v[160:163], v[228:231], v[24:27]
	v_mfma_f32_16x16x32_bf16 v[20:23], v[168:171], v[228:231], v[20:23]
	s_barrier
; #define PG8_STAGE(bufoff, gbase, voff) do { const Src _g = (gbase); _Pragma("unroll") for (int _i = 0; _i < 2; ++_i) \
;         __builtin_amdgcn_raw_ptr_buffer_load_lds(_g.r, (LAS unsigned*)(lds + (bufoff) + ldsw + _i * 8192), 16, (voff)[_i], _g.o, 0, 0); } while (0)
; #define PG8_WAIT_V(n) asm volatile("s_waitcnt vmcnt(" #n ")" ::: "memory")
; template <class Epi, bool ALIGN_EPI, bool SP2, class Hook>
; __device__ __forceinline__ void gemm_phase(LAS unsigned char* lds, const Gemm g, const StaticOrder& S, const Epi& E, Acc& acc, const bool fresh, const Hook& H, const int wave_id) {
;     ...
;         for (int t = t0; t < nt; t += 2) {
;             const bool last = (t == nt - 2);
;             const Src a1 = cA + (size_t)(t + 1) * kstep;
;             const Src a2 = last ? nA : cA + (size_t)(t + 2) * kstep, b2 = last ? nB : cB + (size_t)(t + 2) * kstep;
;             const Src a3 = a2 + kstep, b3 = b2 + kstep;
;             if (last && has_next) H(nxt);
;             if constexpr (SP2) {
;             PG8_TRIP_SP2(PG8_WAIT_V(8));
;             } else {
;             PG8_LDB(B0, 0, 0); PG8_SCHED; PG8_LDA(At, 0, 0); PG8_STAGE(PG8_SA(1, 1), a1 + hstepA, voffA);
;             PG8_WAIT_L(8); PG8_BAR; PG8_WAIT_L(0); PG8_MMA(0, 0, At, B0); PG8_BAR; PG8_SCHED;
;             PG8_LDB(B1, 0, 1); PG8_STAGE(PG8_SB(0, 0), b2, voffB);
;             PG8_BAR; PG8_WAIT_L(0); PG8_MMA(0, 1, At, B1); PG8_BAR;
;             PG8_LDA(At, 0, 1); PG8_STAGE(PG8_SA(0, 0), a2, voffA);
;             PG8_BAR; PG8_WAIT_L(0); PG8_MMA(1, 0, At, B0); PG8_BAR; PG8_SCHED;
;             PG8_STAGE(PG8_SB(0, 1), b2 + hstep, voffB);
;             PG8_WAIT_V(6); PG8_BAR; PG8_MMA(1, 1, At, B1); PG8_BAR;
;             PG8_LDB(B0, 1, 0); PG8_SCHED; PG8_LDA(At, 1, 0); PG8_STAGE(PG8_SA(0, 1), a2 + hstepA, voffA);
;             PG8_WAIT_L(8); PG8_BAR; PG8_WAIT_L(0); PG8_MMA(0, 0, At, B0); PG8_BAR; PG8_SCHED;
;             PG8_LDB(B1, 1, 1); PG8_STAGE(PG8_SB(1, 0), b3, voffB);
;             PG8_BAR; PG8_WAIT_L(0); PG8_MMA(0, 1, At, B1); PG8_BAR;
;             PG8_LDA(At, 1, 1); PG8_STAGE(PG8_SA(1, 0), a3, voffA);
;             PG8_BAR; PG8_WAIT_L(0); PG8_MMA(1, 0, At, B0); PG8_BAR; PG8_SCHED;
;             PG8_STAGE(PG8_SB(1, 1), b3 + hstep, voffB);
;             PG8_WAIT_V(6); PG8_BAR; PG8_MMA(1, 1, At, B1); PG8_BAR;
;             }
;         }
;         if constexpr (ALIGN_EPI) { if (wr == 0) PG8_BAR; }
	s_setprio 0
	s_mov_b32 m0, s44
	s_nop 0
	buffer_load_dwordx4 v144, s[16:19], s60 offen lds
	s_mov_b32 m0, s36
	s_nop 0
	buffer_load_dwordx4 v146, s[16:19], s60 offen lds
	v_add_u32_e32 v152, 0x18000, v148
	v_add_u32_e32 v153, 0x1c000, v148
	ds_read_b128 v[132:135], v152
	ds_read_b128 v[136:139], v152 offset:1024
	ds_read_b128 v[140:143], v152 offset:2048
	ds_read_b128 v[154:157], v152 offset:3072
	ds_read_b128 v[158:161], v153
	ds_read_b128 v[162:165], v153 offset:1024
	ds_read_b128 v[166:169], v153 offset:2048
	ds_read_b128 v[170:173], v153 offset:3072
	s_add_i32 s60, s60, 0x40000
	s_mov_b32 m0, s37
	ds_read_b128 v[174:177], v149 offset:32768
	ds_read_b128 v[178:181], v149 offset:33792
	ds_read_b128 v[182:185], v149 offset:34816
	ds_read_b128 v[186:189], v149 offset:35840
	ds_read_b128 v[190:193], v149 offset:36864
	ds_read_b128 v[212:215], v149 offset:37888
	ds_read_b128 v[216:219], v149 offset:38912
	ds_read_b128 v[228:231], v149 offset:39936
	buffer_load_dwordx4 v144, s[16:19], s60 offen lds
	s_mov_b32 m0, s38
	s_nop 0
	buffer_load_dwordx4 v146, s[16:19], s60 offen lds
	s_waitcnt vmcnt(8)
	s_waitcnt lgkmcnt(0)
	s_setprio 1
	s_barrier
	v_mfma_f32_16x16x32_bf16 v[120:123], v[132:135], v[174:177], v[120:123]
	v_mfma_f32_16x16x32_bf16 v[112:115], v[140:143], v[174:177], v[112:115]
	v_mfma_f32_16x16x32_bf16 v[100:103], v[132:135], v[182:185], v[100:103]
	v_mfma_f32_16x16x32_bf16 v[88:91], v[140:143], v[182:185], v[88:91]
	v_mfma_f32_16x16x32_bf16 v[68:71], v[132:135], v[190:193], v[68:71]
	v_mfma_f32_16x16x32_bf16 v[56:59], v[140:143], v[190:193], v[56:59]
	v_mfma_f32_16x16x32_bf16 v[36:39], v[132:135], v[216:219], v[36:39]
	v_mfma_f32_16x16x32_bf16 v[28:31], v[140:143], v[216:219], v[28:31]
	v_mfma_f32_16x16x32_bf16 v[120:123], v[136:139], v[178:181], v[120:123]
	v_mfma_f32_16x16x32_bf16 v[112:115], v[154:157], v[178:181], v[112:115]
	v_mfma_f32_16x16x32_bf16 v[100:103], v[136:139], v[186:189], v[100:103]
	v_mfma_f32_16x16x32_bf16 v[88:91], v[154:157], v[186:189], v[88:91]
	v_mfma_f32_16x16x32_bf16 v[68:71], v[136:139], v[212:215], v[68:71]
	v_mfma_f32_16x16x32_bf16 v[56:59], v[154:157], v[212:215], v[56:59]
	v_mfma_f32_16x16x32_bf16 v[36:39], v[136:139], v[228:231], v[36:39]
	v_mfma_f32_16x16x32_bf16 v[28:31], v[154:157], v[228:231], v[28:31]
	v_mfma_f32_16x16x32_bf16 v[128:131], v[158:161], v[174:177], v[128:131]
	v_mfma_f32_16x16x32_bf16 v[124:127], v[166:169], v[174:177], v[124:127]
	v_mfma_f32_16x16x32_bf16 v[116:119], v[158:161], v[182:185], v[116:119]
	v_mfma_f32_16x16x32_bf16 v[108:111], v[166:169], v[182:185], v[108:111]
	v_mfma_f32_16x16x32_bf16 v[92:95], v[158:161], v[190:193], v[92:95]
	v_mfma_f32_16x16x32_bf16 v[80:83], v[166:169], v[190:193], v[80:83]
	v_mfma_f32_16x16x32_bf16 v[64:67], v[158:161], v[216:219], v[64:67]
	v_mfma_f32_16x16x32_bf16 v[48:51], v[166:169], v[216:219], v[48:51]
	v_mfma_f32_16x16x32_bf16 v[128:131], v[162:165], v[178:181], v[128:131]
	v_mfma_f32_16x16x32_bf16 v[124:127], v[170:173], v[178:181], v[124:127]
	v_mfma_f32_16x16x32_bf16 v[116:119], v[162:165], v[186:189], v[116:119]
	v_mfma_f32_16x16x32_bf16 v[108:111], v[170:173], v[186:189], v[108:111]
	v_mfma_f32_16x16x32_bf16 v[92:95], v[162:165], v[212:215], v[92:95]
	v_mfma_f32_16x16x32_bf16 v[80:83], v[170:173], v[212:215], v[80:83]
	v_mfma_f32_16x16x32_bf16 v[64:67], v[162:165], v[228:231], v[64:67]
	v_mfma_f32_16x16x32_bf16 v[48:51], v[170:173], v[228:231], v[48:51]
	s_barrier
	s_setprio 0
	s_mov_b32 m0, s39
	s_or_b32 s60, s58, 0x80
	ds_read_b128 v[174:177], v149 offset:49152
	ds_read_b128 v[178:181], v149 offset:50176
	ds_read_b128 v[182:185], v149 offset:51200
	ds_read_b128 v[186:189], v149 offset:52224
	ds_read_b128 v[190:193], v149 offset:53248
	ds_read_b128 v[212:215], v149 offset:54272
	ds_read_b128 v[216:219], v149 offset:55296
	ds_read_b128 v[228:231], v149 offset:56320
	buffer_load_dwordx4 v145, s[12:15], s60 offen lds
	s_mov_b32 m0, s40
	s_add_i32 s58, s58, 0x40080
	buffer_load_dwordx4 v147, s[12:15], s60 offen lds
	s_mov_b32 m0, s43
	s_nop 0
	buffer_load_dwordx4 v145, s[12:15], s58 offen lds
	s_mov_b32 m0, s42
	s_nop 0
	buffer_load_dwordx4 v147, s[12:15], s58 offen lds
	s_add_i32 s29, s29, 2
	s_addk_i32 s56, 0x100
	s_addk_i32 s57, 0x100
	s_cmp_gt_u32 s29, 13
	s_waitcnt vmcnt(6)
	s_waitcnt lgkmcnt(0)
	s_setprio 1
	s_barrier
	v_mfma_f32_16x16x32_bf16 v[72:75], v[132:135], v[174:177], v[72:75]
	v_mfma_f32_16x16x32_bf16 v[60:63], v[140:143], v[174:177], v[60:63]
	v_mfma_f32_16x16x32_bf16 v[40:43], v[132:135], v[182:185], v[40:43]
	v_mfma_f32_16x16x32_bf16 v[32:35], v[140:143], v[182:185], v[32:35]
	v_mfma_f32_16x16x32_bf16 v[16:19], v[132:135], v[190:193], v[16:19]
	v_mfma_f32_16x16x32_bf16 v[12:15], v[140:143], v[190:193], v[12:15]
	v_mfma_f32_16x16x32_bf16 v[6:9], v[132:135], v[216:219], v[8:11]
	v_mfma_f32_16x16x32_bf16 v[2:5], v[140:143], v[216:219], v[2:5]
	v_mfma_f32_16x16x32_bf16 v[72:75], v[136:139], v[178:181], v[72:75]
	v_mfma_f32_16x16x32_bf16 v[60:63], v[154:157], v[178:181], v[60:63]
	v_mfma_f32_16x16x32_bf16 v[40:43], v[136:139], v[186:189], v[40:43]
	v_mfma_f32_16x16x32_bf16 v[32:35], v[154:157], v[186:189], v[32:35]
	v_mfma_f32_16x16x32_bf16 v[16:19], v[136:139], v[212:215], v[16:19]
	v_mfma_f32_16x16x32_bf16 v[12:15], v[154:157], v[212:215], v[12:15]
	v_mfma_f32_16x16x32_bf16 v[8:11], v[136:139], v[228:231], v[6:9]
	v_mfma_f32_16x16x32_bf16 v[4:7], v[154:157], v[228:231], v[2:5]
	v_mfma_f32_16x16x32_bf16 v[96:99], v[158:161], v[174:177], v[96:99]
	v_mfma_f32_16x16x32_bf16 v[104:107], v[166:169], v[174:177], v[104:107]
	v_mfma_f32_16x16x32_bf16 v[84:87], v[158:161], v[182:185], v[84:87]
	v_mfma_f32_16x16x32_bf16 v[76:79], v[166:169], v[182:185], v[76:79]
	v_mfma_f32_16x16x32_bf16 v[52:55], v[158:161], v[190:193], v[52:55]
	v_mfma_f32_16x16x32_bf16 v[44:47], v[166:169], v[190:193], v[44:47]
	v_mfma_f32_16x16x32_bf16 v[24:27], v[158:161], v[216:219], v[24:27]
	v_mfma_f32_16x16x32_bf16 v[20:23], v[166:169], v[216:219], v[20:23]
	v_mfma_f32_16x16x32_bf16 v[96:99], v[162:165], v[178:181], v[96:99]
	v_mfma_f32_16x16x32_bf16 v[104:107], v[170:173], v[178:181], v[104:107]
	v_mfma_f32_16x16x32_bf16 v[84:87], v[162:165], v[186:189], v[84:87]
	v_mfma_f32_16x16x32_bf16 v[76:79], v[170:173], v[186:189], v[76:79]
	v_mfma_f32_16x16x32_bf16 v[52:55], v[162:165], v[212:215], v[52:55]
	v_mfma_f32_16x16x32_bf16 v[44:47], v[170:173], v[212:215], v[44:47]
	v_mfma_f32_16x16x32_bf16 v[24:27], v[162:165], v[228:231], v[24:27]
	v_mfma_f32_16x16x32_bf16 v[20:23], v[170:173], v[228:231], v[20:23]
	s_barrier
	s_setprio 0
	s_cbranch_scc0 .LBB0_391
	s_mov_b32 m0, s41
	s_nop 0
	buffer_load_dwordx4 v144, s[16:19], s59 offen lds
	s_mov_b32 m0, s33
	s_nop 0
	buffer_load_dwordx4 v146, s[16:19], s59 offen lds
	v_readlane_b32 s8, v251, 45
	v_readlane_b32 s9, v251, 46
	s_and_b64 vcc, exec, s[8:9]
	s_cbranch_vccz .LBB0_394
	s_barrier

; #define PG8_WAIT_V(n) asm volatile("s_waitcnt vmcnt(" #n ")" ::: "memory")
; template <class Epi, bool ALIGN_EPI, bool SP2, class Hook>
; __device__ __forceinline__ void gemm_phase(LAS unsigned char* lds, const Gemm g, const StaticOrder& S, const Epi& E, Acc& acc, const bool fresh, const Hook& H, const int wave_id) {
;     ...
;         for (int t = t0; t < nt; t += 2) {
;             const bool last = (t == nt - 2);
;             const Src a1 = cA + (size_t)(t + 1) * kstep;
;             const Src a2 = last ? nA : cA + (size_t)(t + 2) * kstep, b2 = last ? nB : cB + (size_t)(t + 2) * kstep;
;             const Src a3 = a2 + kstep, b3 = b2 + kstep;
;             if (last && has_next) H(nxt);
;             if constexpr (SP2) {
;             PG8_TRIP_SP2(PG8_WAIT_V(8));
.LBB0_903:
	s_add_i32 s100, s55, 0xfffe0000
	v_add_u32_e32 v70, 0x10000, v216
	v_add_u32_e32 v118, 0x14000, v216
	ds_read_b128 v[34:37], v70
	ds_read_b128 v[46:49], v70 offset:1024
	ds_read_b128 v[58:61], v70 offset:2048
	ds_read_b128 v[70:73], v70 offset:3072
	ds_read_b128 v[82:85], v118
	ds_read_b128 v[94:97], v118 offset:1024
	ds_read_b128 v[106:109], v118 offset:2048
	ds_read_b128 v[118:121], v118 offset:3072
	s_mov_b32 m0, s41
	s_nop 0
	buffer_load_dwordx4 v0, s[8:11], s100 offen lds
	s_mov_b32 m0, s33
	s_nop 0
	buffer_load_dwordx4 v214, s[8:11], s100 offen lds
	s_mov_b32 m0, s45
	ds_read_b128 v[130:133], v217
	ds_read_b128 v[142:145], v217 offset:1024
	ds_read_b128 v[154:157], v217 offset:2048
	ds_read_b128 v[166:169], v217 offset:3072
	ds_read_b128 v[174:177], v217 offset:4096
	ds_read_b128 v[182:185], v217 offset:5120
	ds_read_b128 v[186:189], v217 offset:6144
	ds_read_b128 v[190:193], v217 offset:7168
	buffer_load_dwordx4 v0, s[8:11], s55 offen lds
	s_mov_b32 m0, s46
	s_nop 0
	buffer_load_dwordx4 v214, s[8:11], s55 offen lds
	s_waitcnt vmcnt(8)
	s_waitcnt lgkmcnt(0)
	s_setprio 1
	s_barrier
	v_mfma_f32_16x16x32_bf16 v[178:181], v[34:37], v[130:133], v[178:181]
	v_mfma_f32_16x16x32_bf16 v[170:173], v[58:61], v[130:133], v[170:173]
	v_mfma_f32_16x16x32_bf16 v[150:153], v[34:37], v[154:157], v[150:153]
	v_mfma_f32_16x16x32_bf16 v[146:149], v[58:61], v[154:157], v[146:149]
	v_mfma_f32_16x16x32_bf16 v[126:129], v[34:37], v[174:177], v[126:129]
	v_mfma_f32_16x16x32_bf16 v[122:125], v[58:61], v[174:177], v[122:125]
	v_mfma_f32_16x16x32_bf16 v[102:105], v[34:37], v[186:189], v[102:105]
	v_mfma_f32_16x16x32_bf16 v[98:101], v[58:61], v[186:189], v[98:101]
	v_mfma_f32_16x16x32_bf16 v[178:181], v[46:49], v[142:145], v[178:181]
	v_mfma_f32_16x16x32_bf16 v[170:173], v[70:73], v[142:145], v[170:173]
	v_mfma_f32_16x16x32_bf16 v[150:153], v[46:49], v[166:169], v[150:153]
	v_mfma_f32_16x16x32_bf16 v[146:149], v[70:73], v[166:169], v[146:149]
	v_mfma_f32_16x16x32_bf16 v[126:129], v[46:49], v[182:185], v[126:129]
	v_mfma_f32_16x16x32_bf16 v[122:125], v[70:73], v[182:185], v[122:125]
	v_mfma_f32_16x16x32_bf16 v[102:105], v[46:49], v[190:193], v[102:105]
	v_mfma_f32_16x16x32_bf16 v[98:101], v[70:73], v[190:193], v[98:101]
	v_mfma_f32_16x16x32_bf16 v[162:165], v[82:85], v[130:133], v[162:165]
	v_mfma_f32_16x16x32_bf16 v[138:141], v[82:85], v[154:157], v[138:141]
	v_mfma_f32_16x16x32_bf16 v[134:137], v[106:109], v[154:157], v[134:137]
	v_mfma_f32_16x16x32_bf16 v[114:117], v[82:85], v[174:177], v[114:117]
	v_mfma_f32_16x16x32_bf16 v[110:113], v[106:109], v[174:177], v[110:113]
	v_mfma_f32_16x16x32_bf16 v[90:93], v[82:85], v[186:189], v[90:93]
	v_mfma_f32_16x16x32_bf16 v[86:89], v[106:109], v[186:189], v[86:89]
	v_mfma_f32_16x16x32_bf16 v[162:165], v[94:97], v[142:145], v[162:165]
	v_mfma_f32_16x16x32_bf16 v[130:133], v[106:109], v[130:133], v[158:161]
	v_mfma_f32_16x16x32_bf16 v[138:141], v[94:97], v[166:169], v[138:141]
	v_mfma_f32_16x16x32_bf16 v[134:137], v[118:121], v[166:169], v[134:137]
	v_mfma_f32_16x16x32_bf16 v[114:117], v[94:97], v[182:185], v[114:117]
	v_mfma_f32_16x16x32_bf16 v[110:113], v[118:121], v[182:185], v[110:113]
	v_mfma_f32_16x16x32_bf16 v[90:93], v[94:97], v[190:193], v[90:93]
	v_mfma_f32_16x16x32_bf16 v[86:89], v[118:121], v[190:193], v[86:89]
	v_mfma_f32_16x16x32_bf16 v[130:133], v[118:121], v[142:145], v[130:133]
	s_barrier
	s_setprio 0
	s_add_i32 s12, s55, 0xfffe0080
	s_cmp_eq_u32 s57, 4
	s_cselect_b32 s60, s53, s12
	s_cselect_b32 s13, s29, s77
	s_cselect_b32 s12, s28, s76
	s_cselect_b32 s15, s31, s35
	s_cselect_b32 s14, s30, s34
	s_cselect_b32 s58, s54, s56
	s_cselect_b32 s16, s2, s8
	s_cselect_b32 s17, s3, s9
	s_cselect_b32 s18, s26, s10
	s_cselect_b32 s19, s27, s11
	s_or_b32 s59, s60, 0x80
	s_mov_b32 m0, s92
	ds_read_b128 v[142:145], v217 offset:16384
	ds_read_b128 v[154:157], v217 offset:17408
	ds_read_b128 v[158:161], v217 offset:18432
	ds_read_b128 v[166:169], v217 offset:19456
	ds_read_b128 v[174:177], v217 offset:20480
	ds_read_b128 v[182:185], v217 offset:21504
	ds_read_b128 v[186:189], v217 offset:22528
	ds_read_b128 v[190:193], v217 offset:23552
	buffer_load_dwordx4 v199, s[12:15], s58 offen lds
	s_mov_b32 m0, s93
	s_add_i32 s61, s58, 0x20000
	buffer_load_dwordx4 v215, s[12:15], s58 offen lds
	s_mov_b32 m0, s94
	s_nop 0
	buffer_load_dwordx4 v199, s[12:15], s61 offen lds
	s_mov_b32 m0, s95
	s_nop 0
	buffer_load_dwordx4 v215, s[12:15], s61 offen lds
	s_waitcnt vmcnt(6)
	s_waitcnt lgkmcnt(0)
	s_setprio 1
	s_barrier
	v_mfma_f32_16x16x32_bf16 v[78:81], v[34:37], v[142:145], v[78:81]
	v_mfma_f32_16x16x32_bf16 v[74:77], v[58:61], v[142:145], v[74:77]
	v_mfma_f32_16x16x32_bf16 v[54:57], v[34:37], v[158:161], v[54:57]
	v_mfma_f32_16x16x32_bf16 v[50:53], v[58:61], v[158:161], v[50:53]
	v_mfma_f32_16x16x32_bf16 v[30:33], v[34:37], v[174:177], v[30:33]
	v_mfma_f32_16x16x32_bf16 v[26:29], v[58:61], v[174:177], v[26:29]
	v_mfma_f32_16x16x32_bf16 v[14:17], v[34:37], v[186:189], v[14:17]
	v_mfma_f32_16x16x32_bf16 v[10:13], v[58:61], v[186:189], v[10:13]
	v_mfma_f32_16x16x32_bf16 v[78:81], v[46:49], v[154:157], v[78:81]
	v_mfma_f32_16x16x32_bf16 v[74:77], v[70:73], v[154:157], v[74:77]
	v_mfma_f32_16x16x32_bf16 v[54:57], v[46:49], v[166:169], v[54:57]
	v_mfma_f32_16x16x32_bf16 v[50:53], v[70:73], v[166:169], v[50:53]
	v_mfma_f32_16x16x32_bf16 v[30:33], v[46:49], v[182:185], v[30:33]
	v_mfma_f32_16x16x32_bf16 v[26:29], v[70:73], v[182:185], v[26:29]
	v_mfma_f32_16x16x32_bf16 v[14:17], v[46:49], v[190:193], v[14:17]
	v_mfma_f32_16x16x32_bf16 v[10:13], v[70:73], v[190:193], v[10:13]
	v_mfma_f32_16x16x32_bf16 v[42:45], v[82:85], v[158:161], v[42:45]
	v_mfma_f32_16x16x32_bf16 v[38:41], v[106:109], v[158:161], v[38:41]
	v_mfma_f32_16x16x32_bf16 v[22:25], v[82:85], v[174:177], v[22:25]
	v_mfma_f32_16x16x32_bf16 v[18:21], v[106:109], v[174:177], v[18:21]
	v_mfma_f32_16x16x32_bf16 v[6:9], v[82:85], v[186:189], v[6:9]
	v_mfma_f32_16x16x32_bf16 v[2:5], v[106:109], v[186:189], v[2:5]
	v_mfma_f32_16x16x32_bf16 v[34:37], v[82:85], v[142:145], v[66:69]
	v_mfma_f32_16x16x32_bf16 v[46:49], v[106:109], v[142:145], v[62:65]
	v_mfma_f32_16x16x32_bf16 v[42:45], v[94:97], v[166:169], v[42:45]
	v_mfma_f32_16x16x32_bf16 v[38:41], v[118:121], v[166:169], v[38:41]
	v_mfma_f32_16x16x32_bf16 v[22:25], v[94:97], v[182:185], v[22:25]
	v_mfma_f32_16x16x32_bf16 v[18:21], v[118:121], v[182:185], v[18:21]
	v_mfma_f32_16x16x32_bf16 v[6:9], v[94:97], v[190:193], v[6:9]
	v_mfma_f32_16x16x32_bf16 v[2:5], v[118:121], v[190:193], v[2:5]
	v_mfma_f32_16x16x32_bf16 v[34:37], v[94:97], v[154:157], v[34:37]
	v_mfma_f32_16x16x32_bf16 v[46:49], v[118:121], v[154:157], v[46:49]
	s_barrier
; #define PG8_STAGE(bufoff, gbase, voff) do { const Src _g = (gbase); _Pragma("unroll") for (int _i = 0; _i < 2; ++_i) \
;         __builtin_amdgcn_raw_ptr_buffer_load_lds(_g.r, (LAS unsigned*)(lds + (bufoff) + ldsw + _i * 8192), 16, (voff)[_i], _g.o, 0, 0); } while (0)
; #define PG8_WAIT_V(n) asm volatile("s_waitcnt vmcnt(" #n ")" ::: "memory")
; template <class Epi, bool ALIGN_EPI, bool SP2, class Hook>
; __device__ __forceinline__ void gemm_phase(LAS unsigned char* lds, const Gemm g, const StaticOrder& S, const Epi& E, Acc& acc, const bool fresh, const Hook& H, const int wave_id) {
;     ...
;         for (int t = t0; t < nt; t += 2) {
;             const bool last = (t == nt - 2);
;             const Src a1 = cA + (size_t)(t + 1) * kstep;
;             const Src a2 = last ? nA : cA + (size_t)(t + 2) * kstep, b2 = last ? nB : cB + (size_t)(t + 2) * kstep;
;             const Src a3 = a2 + kstep, b3 = b2 + kstep;
;             if (last && has_next) H(nxt);
;             if constexpr (SP2) {
;             PG8_TRIP_SP2(PG8_WAIT_V(8));
;             } else {
;             PG8_LDB(B0, 0, 0); PG8_SCHED; PG8_LDA(At, 0, 0); PG8_STAGE(PG8_SA(1, 1), a1 + hstepA, voffA);
;             PG8_WAIT_L(8); PG8_BAR; PG8_WAIT_L(0); PG8_MMA(0, 0, At, B0); PG8_BAR; PG8_SCHED;
;             PG8_LDB(B1, 0, 1); PG8_STAGE(PG8_SB(0, 0), b2, voffB);
;             PG8_BAR; PG8_WAIT_L(0); PG8_MMA(0, 1, At, B1); PG8_BAR;
;             PG8_LDA(At, 0, 1); PG8_STAGE(PG8_SA(0, 0), a2, voffA);
;             PG8_BAR; PG8_WAIT_L(0); PG8_MMA(1, 0, At, B0); PG8_BAR; PG8_SCHED;
;             PG8_STAGE(PG8_SB(0, 1), b2 + hstep, voffB);
;             PG8_WAIT_V(6); PG8_BAR; PG8_MMA(1, 1, At, B1); PG8_BAR;
;             PG8_LDB(B0, 1, 0); PG8_SCHED; PG8_LDA(At, 1, 0); PG8_STAGE(PG8_SA(0, 1), a2 + hstepA, voffA);
;             PG8_WAIT_L(8); PG8_BAR; PG8_WAIT_L(0); PG8_MMA(0, 0, At, B0); PG8_BAR; PG8_SCHED;
;             PG8_LDB(B1, 1, 1); PG8_STAGE(PG8_SB(1, 0), b3, voffB);
;             PG8_BAR; PG8_WAIT_L(0); PG8_MMA(0, 1, At, B1); PG8_BAR;
;             PG8_LDA(At, 1, 1); PG8_STAGE(PG8_SA(1, 0), a3, voffA);
;             PG8_BAR; PG8_WAIT_L(0); PG8_MMA(1, 0, At, B0); PG8_BAR; PG8_SCHED;
;             PG8_STAGE(PG8_SB(1, 1), b3 + hstep, voffB);
;             PG8_WAIT_V(6); PG8_BAR; PG8_MMA(1, 1, At, B1); PG8_BAR;
;             }
;         }
;         if constexpr (ALIGN_EPI) { if (wr == 0) PG8_BAR; }
	s_setprio 0
	s_mov_b32 m0, s44
	s_nop 0
	buffer_load_dwordx4 v0, s[16:19], s60 offen lds
	s_mov_b32 m0, s36
	s_nop 0
	buffer_load_dwordx4 v214, s[16:19], s60 offen lds
	v_add_u32_e32 v70, 0x18000, v216
	v_add_u32_e32 v118, 0x1c000, v216
	ds_read_b128 v[58:61], v70
	ds_read_b128 v[62:65], v70 offset:1024
	ds_read_b128 v[66:69], v70 offset:2048
	ds_read_b128 v[70:73], v70 offset:3072
	ds_read_b128 v[82:85], v118
	ds_read_b128 v[94:97], v118 offset:1024
	ds_read_b128 v[106:109], v118 offset:2048
	ds_read_b128 v[118:121], v118 offset:3072
	s_add_i32 s60, s60, 0x20000
	s_mov_b32 m0, s37
	ds_read_b128 v[142:145], v217 offset:32768
	ds_read_b128 v[154:157], v217 offset:33792
	ds_read_b128 v[166:169], v217 offset:34816
	ds_read_b128 v[174:177], v217 offset:35840
	ds_read_b128 v[182:185], v217 offset:36864
	ds_read_b128 v[186:189], v217 offset:37888
	ds_read_b128 v[190:193], v217 offset:38912
	ds_read_b128 v[194:197], v217 offset:39936
	buffer_load_dwordx4 v0, s[16:19], s60 offen lds
	s_mov_b32 m0, s38
	s_nop 0
	buffer_load_dwordx4 v214, s[16:19], s60 offen lds
	s_waitcnt vmcnt(8)
	s_waitcnt lgkmcnt(0)
	s_setprio 1
	s_barrier
	v_mfma_f32_16x16x32_bf16 v[158:161], v[58:61], v[142:145], v[178:181]
	v_mfma_f32_16x16x32_bf16 v[178:181], v[62:65], v[154:157], v[158:161]
	v_mfma_f32_16x16x32_bf16 v[158:161], v[66:69], v[142:145], v[170:173]
	v_mfma_f32_16x16x32_bf16 v[150:153], v[58:61], v[166:169], v[150:153]
	v_mfma_f32_16x16x32_bf16 v[146:149], v[66:69], v[166:169], v[146:149]
	v_mfma_f32_16x16x32_bf16 v[126:129], v[58:61], v[182:185], v[126:129]
	v_mfma_f32_16x16x32_bf16 v[122:125], v[66:69], v[182:185], v[122:125]
	v_mfma_f32_16x16x32_bf16 v[102:105], v[58:61], v[190:193], v[102:105]
	v_mfma_f32_16x16x32_bf16 v[98:101], v[66:69], v[190:193], v[98:101]
	v_mfma_f32_16x16x32_bf16 v[170:173], v[70:73], v[154:157], v[158:161]
	v_mfma_f32_16x16x32_bf16 v[150:153], v[62:65], v[174:177], v[150:153]
	v_mfma_f32_16x16x32_bf16 v[146:149], v[70:73], v[174:177], v[146:149]
	v_mfma_f32_16x16x32_bf16 v[126:129], v[62:65], v[186:189], v[126:129]
	v_mfma_f32_16x16x32_bf16 v[122:125], v[70:73], v[186:189], v[122:125]
	v_mfma_f32_16x16x32_bf16 v[102:105], v[62:65], v[194:197], v[102:105]
	v_mfma_f32_16x16x32_bf16 v[98:101], v[70:73], v[194:197], v[98:101]
	v_mfma_f32_16x16x32_bf16 v[158:161], v[82:85], v[142:145], v[162:165]
	v_mfma_f32_16x16x32_bf16 v[130:133], v[106:109], v[142:145], v[130:133]
	v_mfma_f32_16x16x32_bf16 v[162:165], v[94:97], v[154:157], v[158:161]
	v_mfma_f32_16x16x32_bf16 v[158:161], v[118:121], v[154:157], v[130:133]
	v_mfma_f32_16x16x32_bf16 v[130:133], v[82:85], v[166:169], v[138:141]
	v_mfma_f32_16x16x32_bf16 v[138:141], v[94:97], v[174:177], v[130:133]
	v_mfma_f32_16x16x32_bf16 v[130:133], v[106:109], v[166:169], v[134:137]
	v_mfma_f32_16x16x32_bf16 v[114:117], v[82:85], v[182:185], v[114:117]
	v_mfma_f32_16x16x32_bf16 v[110:113], v[106:109], v[182:185], v[110:113]
	v_mfma_f32_16x16x32_bf16 v[90:93], v[82:85], v[190:193], v[90:93]
	v_mfma_f32_16x16x32_bf16 v[86:89], v[106:109], v[190:193], v[86:89]
	v_mfma_f32_16x16x32_bf16 v[134:137], v[118:121], v[174:177], v[130:133]
	v_mfma_f32_16x16x32_bf16 v[114:117], v[94:97], v[186:189], v[114:117]
	v_mfma_f32_16x16x32_bf16 v[110:113], v[118:121], v[186:189], v[110:113]
	v_mfma_f32_16x16x32_bf16 v[90:93], v[94:97], v[194:197], v[90:93]
	v_mfma_f32_16x16x32_bf16 v[86:89], v[118:121], v[194:197], v[86:89]
	s_barrier
	s_setprio 0
	s_mov_b32 m0, s39
	s_or_b32 s60, s58, 0x80
	ds_read_b128 v[130:133], v217 offset:49152
	ds_read_b128 v[142:145], v217 offset:50176
	ds_read_b128 v[154:157], v217 offset:51200
	ds_read_b128 v[166:169], v217 offset:52224
	ds_read_b128 v[174:177], v217 offset:53248
	ds_read_b128 v[182:185], v217 offset:54272
	ds_read_b128 v[186:189], v217 offset:55296
	ds_read_b128 v[190:193], v217 offset:56320
	buffer_load_dwordx4 v199, s[12:15], s60 offen lds
	s_mov_b32 m0, s40
	s_add_i32 s58, s58, 0x20080
	buffer_load_dwordx4 v215, s[12:15], s60 offen lds
	s_mov_b32 m0, s43
	s_nop 0
	buffer_load_dwordx4 v199, s[12:15], s58 offen lds
	s_mov_b32 m0, s42
	s_nop 0
	buffer_load_dwordx4 v215, s[12:15], s58 offen lds
	s_add_i32 s57, s57, 2
	s_addk_i32 s55, 0x100
	s_addk_i32 s56, 0x100
	s_cmp_gt_u32 s57, 5
	s_waitcnt vmcnt(6)
	s_waitcnt lgkmcnt(0)
	s_setprio 1
	s_barrier
	v_mfma_f32_16x16x32_bf16 v[78:81], v[58:61], v[130:133], v[78:81]
	v_mfma_f32_16x16x32_bf16 v[74:77], v[66:69], v[130:133], v[74:77]
	v_mfma_f32_16x16x32_bf16 v[54:57], v[58:61], v[154:157], v[54:57]
	v_mfma_f32_16x16x32_bf16 v[50:53], v[66:69], v[154:157], v[50:53]
	v_mfma_f32_16x16x32_bf16 v[30:33], v[58:61], v[174:177], v[30:33]
	v_mfma_f32_16x16x32_bf16 v[26:29], v[66:69], v[174:177], v[26:29]
	v_mfma_f32_16x16x32_bf16 v[14:17], v[58:61], v[186:189], v[14:17]
	v_mfma_f32_16x16x32_bf16 v[10:13], v[66:69], v[186:189], v[10:13]
	v_mfma_f32_16x16x32_bf16 v[78:81], v[62:65], v[142:145], v[78:81]
	v_mfma_f32_16x16x32_bf16 v[74:77], v[70:73], v[142:145], v[74:77]
	v_mfma_f32_16x16x32_bf16 v[54:57], v[62:65], v[166:169], v[54:57]
	v_mfma_f32_16x16x32_bf16 v[50:53], v[70:73], v[166:169], v[50:53]
	v_mfma_f32_16x16x32_bf16 v[30:33], v[62:65], v[182:185], v[30:33]
	v_mfma_f32_16x16x32_bf16 v[26:29], v[70:73], v[182:185], v[26:29]
	v_mfma_f32_16x16x32_bf16 v[14:17], v[62:65], v[190:193], v[14:17]
	v_mfma_f32_16x16x32_bf16 v[10:13], v[70:73], v[190:193], v[10:13]
	v_mfma_f32_16x16x32_bf16 v[34:37], v[82:85], v[130:133], v[34:37]
	v_mfma_f32_16x16x32_bf16 v[66:69], v[94:97], v[142:145], v[34:37]
	v_mfma_f32_16x16x32_bf16 v[34:37], v[106:109], v[130:133], v[46:49]
	v_mfma_f32_16x16x32_bf16 v[62:65], v[118:121], v[142:145], v[34:37]
	v_mfma_f32_16x16x32_bf16 v[34:37], v[82:85], v[154:157], v[42:45]
	v_mfma_f32_16x16x32_bf16 v[42:45], v[94:97], v[166:169], v[34:37]
	v_mfma_f32_16x16x32_bf16 v[34:37], v[106:109], v[154:157], v[38:41]
	v_mfma_f32_16x16x32_bf16 v[22:25], v[82:85], v[174:177], v[22:25]
	v_mfma_f32_16x16x32_bf16 v[18:21], v[106:109], v[174:177], v[18:21]
	v_mfma_f32_16x16x32_bf16 v[6:9], v[82:85], v[186:189], v[6:9]
	v_mfma_f32_16x16x32_bf16 v[2:5], v[106:109], v[186:189], v[2:5]
	v_mfma_f32_16x16x32_bf16 v[38:41], v[118:121], v[166:169], v[34:37]
	v_mfma_f32_16x16x32_bf16 v[22:25], v[94:97], v[182:185], v[22:25]
	v_mfma_f32_16x16x32_bf16 v[18:21], v[118:121], v[182:185], v[18:21]
	v_mfma_f32_16x16x32_bf16 v[6:9], v[94:97], v[190:193], v[6:9]
	v_mfma_f32_16x16x32_bf16 v[2:5], v[118:121], v[190:193], v[2:5]
	s_barrier
	s_setprio 0
	s_cbranch_scc0 .LBB0_903
	s_mov_b32 m0, s41
	s_nop 0
	buffer_load_dwordx4 v0, s[16:19], s59 offen lds
	s_mov_b32 m0, s33
	s_nop 0
	buffer_load_dwordx4 v214, s[16:19], s59 offen lds
	v_readlane_b32 s8, v251, 45
	v_readlane_b32 s9, v251, 46
	s_and_b64 vcc, exec, s[8:9]
	s_cbranch_vccz .LBB0_906
	s_barrier

; #define PG8_WAIT_V(n) asm volatile("s_waitcnt vmcnt(" #n ")" ::: "memory")
; template <class Epi, bool ALIGN_EPI, bool SP2, class Hook>
; __device__ __forceinline__ void gemm_phase(LAS unsigned char* lds, const Gemm g, const StaticOrder& S, const Epi& E, Acc& acc, const bool fresh, const Hook& H, const int wave_id) {
;     ...
;         for (int t = t0; t < nt; t += 2) {
;             const bool last = (t == nt - 2);
;             const Src a1 = cA + (size_t)(t + 1) * kstep;
;             const Src a2 = last ? nA : cA + (size_t)(t + 2) * kstep, b2 = last ? nB : cB + (size_t)(t + 2) * kstep;
;             const Src a3 = a2 + kstep, b3 = b2 + kstep;
;             if (last && has_next) H(nxt);
;             if constexpr (SP2) {
;             PG8_TRIP_SP2(PG8_WAIT_V(8));
.LBB0_1235:
	s_add_i32 s100, s2, 0xfffc0000
	v_add_u32_e32 v142, 0x10000, v161
	v_add_u32_e32 v163, 0x14000, v161
	ds_read_b128 v[130:133], v142
	ds_read_b128 v[134:137], v142 offset:1024
	ds_read_b128 v[138:141], v142 offset:2048
	ds_read_b128 v[142:145], v142 offset:3072
	ds_read_b128 v[146:149], v163
	ds_read_b128 v[150:153], v163 offset:1024
	ds_read_b128 v[154:157], v163 offset:2048
	ds_read_b128 v[164:167], v163 offset:3072
	s_mov_b32 m0, s41
	s_nop 0
	buffer_load_dwordx4 v0, s[12:15], s100 offen lds
	s_mov_b32 m0, s33
	s_nop 0
	buffer_load_dwordx4 v159, s[12:15], s100 offen lds
	s_mov_b32 m0, s45
	ds_read_b128 v[168:171], v162
	ds_read_b128 v[172:175], v162 offset:1024
	ds_read_b128 v[176:179], v162 offset:2048
	ds_read_b128 v[180:183], v162 offset:3072
	ds_read_b128 v[184:187], v162 offset:4096
	ds_read_b128 v[188:191], v162 offset:5120
	ds_read_b128 v[192:195], v162 offset:6144
	ds_read_b128 v[200:203], v162 offset:7168
	buffer_load_dwordx4 v0, s[12:15], s2 offen lds
	s_mov_b32 m0, s46
	s_nop 0
	buffer_load_dwordx4 v159, s[12:15], s2 offen lds
	s_waitcnt vmcnt(8)
	s_waitcnt lgkmcnt(0)
	s_setprio 1
	s_barrier
	v_mfma_f32_16x16x32_bf16 v[126:129], v[130:133], v[168:171], v[126:129]
	v_mfma_f32_16x16x32_bf16 v[122:125], v[138:141], v[168:171], v[122:125]
	v_mfma_f32_16x16x32_bf16 v[110:113], v[130:133], v[176:179], v[110:113]
	v_mfma_f32_16x16x32_bf16 v[106:109], v[138:141], v[176:179], v[106:109]
	v_mfma_f32_16x16x32_bf16 v[94:97], v[130:133], v[184:187], v[94:97]
	v_mfma_f32_16x16x32_bf16 v[90:93], v[138:141], v[184:187], v[90:93]
	v_mfma_f32_16x16x32_bf16 v[78:81], v[130:133], v[192:195], v[78:81]
	v_mfma_f32_16x16x32_bf16 v[74:77], v[138:141], v[192:195], v[74:77]
	v_mfma_f32_16x16x32_bf16 v[126:129], v[134:137], v[172:175], v[126:129]
	v_mfma_f32_16x16x32_bf16 v[122:125], v[142:145], v[172:175], v[122:125]
	v_mfma_f32_16x16x32_bf16 v[110:113], v[134:137], v[180:183], v[110:113]
	v_mfma_f32_16x16x32_bf16 v[106:109], v[142:145], v[180:183], v[106:109]
	v_mfma_f32_16x16x32_bf16 v[94:97], v[134:137], v[188:191], v[94:97]
	v_mfma_f32_16x16x32_bf16 v[90:93], v[142:145], v[188:191], v[90:93]
	v_mfma_f32_16x16x32_bf16 v[78:81], v[134:137], v[200:203], v[78:81]
	v_mfma_f32_16x16x32_bf16 v[74:77], v[142:145], v[200:203], v[74:77]
	v_mfma_f32_16x16x32_bf16 v[118:121], v[146:149], v[168:171], v[118:121]
	v_mfma_f32_16x16x32_bf16 v[114:117], v[154:157], v[168:171], v[114:117]
	v_mfma_f32_16x16x32_bf16 v[102:105], v[146:149], v[176:179], v[102:105]
	v_mfma_f32_16x16x32_bf16 v[98:101], v[154:157], v[176:179], v[98:101]
	v_mfma_f32_16x16x32_bf16 v[86:89], v[146:149], v[184:187], v[86:89]
	v_mfma_f32_16x16x32_bf16 v[82:85], v[154:157], v[184:187], v[82:85]
	v_mfma_f32_16x16x32_bf16 v[70:73], v[146:149], v[192:195], v[70:73]
	v_mfma_f32_16x16x32_bf16 v[66:69], v[154:157], v[192:195], v[66:69]
	v_mfma_f32_16x16x32_bf16 v[118:121], v[150:153], v[172:175], v[118:121]
	v_mfma_f32_16x16x32_bf16 v[114:117], v[164:167], v[172:175], v[114:117]
	v_mfma_f32_16x16x32_bf16 v[102:105], v[150:153], v[180:183], v[102:105]
	v_mfma_f32_16x16x32_bf16 v[98:101], v[164:167], v[180:183], v[98:101]
	v_mfma_f32_16x16x32_bf16 v[86:89], v[150:153], v[188:191], v[86:89]
	v_mfma_f32_16x16x32_bf16 v[82:85], v[164:167], v[188:191], v[82:85]
	v_mfma_f32_16x16x32_bf16 v[70:73], v[150:153], v[200:203], v[70:73]
	v_mfma_f32_16x16x32_bf16 v[66:69], v[164:167], v[200:203], v[66:69]
	s_barrier
	s_setprio 0
	s_add_i32 s16, s2, 0xfffc0080
	s_cmp_eq_u32 s59, 12
	s_cselect_b32 s62, s55, s16
	s_cselect_b32 s17, s31, s9
	s_cselect_b32 s16, s30, s8
	s_cselect_b32 s19, s35, s51
	s_cselect_b32 s18, s34, s50
	s_cselect_b32 s60, s56, s3
	s_cselect_b32 s20, s26, s12
	s_cselect_b32 s21, s27, s13
	s_cselect_b32 s22, s28, s14
	s_cselect_b32 s23, s29, s15
	s_or_b32 s61, s62, 0x80
	s_mov_b32 m0, s92
	ds_read_b128 v[168:171], v162 offset:16384
	ds_read_b128 v[172:175], v162 offset:17408
	ds_read_b128 v[176:179], v162 offset:18432
	ds_read_b128 v[180:183], v162 offset:19456
	ds_read_b128 v[184:187], v162 offset:20480
	ds_read_b128 v[188:191], v162 offset:21504
	ds_read_b128 v[192:195], v162 offset:22528
	ds_read_b128 v[200:203], v162 offset:23552
	buffer_load_dwordx4 v158, s[16:19], s60 offen lds
	s_mov_b32 m0, s93
	s_add_i32 s63, s60, 0x40000
	buffer_load_dwordx4 v160, s[16:19], s60 offen lds
	s_mov_b32 m0, s94
	s_nop 0
	buffer_load_dwordx4 v158, s[16:19], s63 offen lds
	s_mov_b32 m0, s95
	s_nop 0
	buffer_load_dwordx4 v160, s[16:19], s63 offen lds
	s_waitcnt vmcnt(6)
	s_waitcnt lgkmcnt(0)
	s_setprio 1
	s_barrier
	v_mfma_f32_16x16x32_bf16 v[62:65], v[130:133], v[168:171], v[62:65]
	v_mfma_f32_16x16x32_bf16 v[58:61], v[138:141], v[168:171], v[58:61]
	v_mfma_f32_16x16x32_bf16 v[46:49], v[130:133], v[176:179], v[46:49]
	v_mfma_f32_16x16x32_bf16 v[42:45], v[138:141], v[176:179], v[42:45]
	v_mfma_f32_16x16x32_bf16 v[30:33], v[130:133], v[184:187], v[30:33]
	v_mfma_f32_16x16x32_bf16 v[26:29], v[138:141], v[184:187], v[26:29]
	v_mfma_f32_16x16x32_bf16 v[14:17], v[130:133], v[192:195], v[14:17]
	v_mfma_f32_16x16x32_bf16 v[10:13], v[138:141], v[192:195], v[10:13]
	v_mfma_f32_16x16x32_bf16 v[62:65], v[134:137], v[172:175], v[62:65]
	v_mfma_f32_16x16x32_bf16 v[58:61], v[142:145], v[172:175], v[58:61]
	v_mfma_f32_16x16x32_bf16 v[46:49], v[134:137], v[180:183], v[46:49]
	v_mfma_f32_16x16x32_bf16 v[42:45], v[142:145], v[180:183], v[42:45]
	v_mfma_f32_16x16x32_bf16 v[30:33], v[134:137], v[188:191], v[30:33]
	v_mfma_f32_16x16x32_bf16 v[26:29], v[142:145], v[188:191], v[26:29]
	v_mfma_f32_16x16x32_bf16 v[14:17], v[134:137], v[200:203], v[14:17]
	v_mfma_f32_16x16x32_bf16 v[10:13], v[142:145], v[200:203], v[10:13]
	v_mfma_f32_16x16x32_bf16 v[54:57], v[146:149], v[168:171], v[54:57]
	v_mfma_f32_16x16x32_bf16 v[50:53], v[154:157], v[168:171], v[50:53]
	v_mfma_f32_16x16x32_bf16 v[38:41], v[146:149], v[176:179], v[38:41]
	v_mfma_f32_16x16x32_bf16 v[34:37], v[154:157], v[176:179], v[34:37]
	v_mfma_f32_16x16x32_bf16 v[22:25], v[146:149], v[184:187], v[22:25]
	v_mfma_f32_16x16x32_bf16 v[18:21], v[154:157], v[184:187], v[18:21]
	v_mfma_f32_16x16x32_bf16 v[6:9], v[146:149], v[192:195], v[6:9]
	v_mfma_f32_16x16x32_bf16 v[2:5], v[154:157], v[192:195], v[2:5]
	v_mfma_f32_16x16x32_bf16 v[54:57], v[150:153], v[172:175], v[54:57]
	v_mfma_f32_16x16x32_bf16 v[50:53], v[164:167], v[172:175], v[50:53]
	v_mfma_f32_16x16x32_bf16 v[38:41], v[150:153], v[180:183], v[38:41]
	v_mfma_f32_16x16x32_bf16 v[34:37], v[164:167], v[180:183], v[34:37]
	v_mfma_f32_16x16x32_bf16 v[22:25], v[150:153], v[188:191], v[22:25]
	v_mfma_f32_16x16x32_bf16 v[18:21], v[164:167], v[188:191], v[18:21]
	v_mfma_f32_16x16x32_bf16 v[6:9], v[150:153], v[200:203], v[6:9]
	v_mfma_f32_16x16x32_bf16 v[2:5], v[164:167], v[200:203], v[2:5]
	s_barrier
	s_setprio 0
	s_mov_b32 m0, s44
	s_nop 0
	buffer_load_dwordx4 v0, s[20:23], s62 offen lds
	s_mov_b32 m0, s36
	s_nop 0
	buffer_load_dwordx4 v159, s[20:23], s62 offen lds
	v_add_u32_e32 v142, 0x18000, v161
	v_add_u32_e32 v163, 0x1c000, v161
	ds_read_b128 v[130:133], v142
	ds_read_b128 v[134:137], v142 offset:1024
	ds_read_b128 v[138:141], v142 offset:2048
	ds_read_b128 v[142:145], v142 offset:3072
	ds_read_b128 v[146:149], v163
	ds_read_b128 v[150:153], v163 offset:1024
	ds_read_b128 v[154:157], v163 offset:2048
	ds_read_b128 v[164:167], v163 offset:3072
	s_add_i32 s62, s62, 0x40000
	s_mov_b32 m0, s37
	ds_read_b128 v[168:171], v162 offset:32768
	ds_read_b128 v[172:175], v162 offset:33792
	ds_read_b128 v[176:179], v162 offset:34816
	ds_read_b128 v[180:183], v162 offset:35840
	ds_read_b128 v[184:187], v162 offset:36864
	ds_read_b128 v[188:191], v162 offset:37888
	ds_read_b128 v[192:195], v162 offset:38912
	ds_read_b128 v[200:203], v162 offset:39936
	buffer_load_dwordx4 v0, s[20:23], s62 offen lds
	s_mov_b32 m0, s38
	s_nop 0
	buffer_load_dwordx4 v159, s[20:23], s62 offen lds
	s_waitcnt vmcnt(8)
	s_waitcnt lgkmcnt(0)
	s_setprio 1
	s_barrier
	v_mfma_f32_16x16x32_bf16 v[126:129], v[130:133], v[168:171], v[126:129]
	v_mfma_f32_16x16x32_bf16 v[122:125], v[138:141], v[168:171], v[122:125]
	v_mfma_f32_16x16x32_bf16 v[110:113], v[130:133], v[176:179], v[110:113]
	v_mfma_f32_16x16x32_bf16 v[106:109], v[138:141], v[176:179], v[106:109]
	v_mfma_f32_16x16x32_bf16 v[94:97], v[130:133], v[184:187], v[94:97]
	v_mfma_f32_16x16x32_bf16 v[90:93], v[138:141], v[184:187], v[90:93]
	v_mfma_f32_16x16x32_bf16 v[78:81], v[130:133], v[192:195], v[78:81]
	v_mfma_f32_16x16x32_bf16 v[74:77], v[138:141], v[192:195], v[74:77]
	v_mfma_f32_16x16x32_bf16 v[126:129], v[134:137], v[172:175], v[126:129]
	v_mfma_f32_16x16x32_bf16 v[122:125], v[142:145], v[172:175], v[122:125]
	v_mfma_f32_16x16x32_bf16 v[110:113], v[134:137], v[180:183], v[110:113]
	v_mfma_f32_16x16x32_bf16 v[106:109], v[142:145], v[180:183], v[106:109]
	v_mfma_f32_16x16x32_bf16 v[94:97], v[134:137], v[188:191], v[94:97]
	v_mfma_f32_16x16x32_bf16 v[90:93], v[142:145], v[188:191], v[90:93]
	v_mfma_f32_16x16x32_bf16 v[78:81], v[134:137], v[200:203], v[78:81]
	v_mfma_f32_16x16x32_bf16 v[74:77], v[142:145], v[200:203], v[74:77]
	v_mfma_f32_16x16x32_bf16 v[118:121], v[146:149], v[168:171], v[118:121]
	v_mfma_f32_16x16x32_bf16 v[114:117], v[154:157], v[168:171], v[114:117]
	v_mfma_f32_16x16x32_bf16 v[102:105], v[146:149], v[176:179], v[102:105]
	v_mfma_f32_16x16x32_bf16 v[98:101], v[154:157], v[176:179], v[98:101]
	v_mfma_f32_16x16x32_bf16 v[86:89], v[146:149], v[184:187], v[86:89]
	v_mfma_f32_16x16x32_bf16 v[82:85], v[154:157], v[184:187], v[82:85]
	v_mfma_f32_16x16x32_bf16 v[70:73], v[146:149], v[192:195], v[70:73]
	v_mfma_f32_16x16x32_bf16 v[66:69], v[154:157], v[192:195], v[66:69]
	v_mfma_f32_16x16x32_bf16 v[118:121], v[150:153], v[172:175], v[118:121]
	v_mfma_f32_16x16x32_bf16 v[114:117], v[164:167], v[172:175], v[114:117]
	v_mfma_f32_16x16x32_bf16 v[102:105], v[150:153], v[180:183], v[102:105]
	v_mfma_f32_16x16x32_bf16 v[98:101], v[164:167], v[180:183], v[98:101]
	v_mfma_f32_16x16x32_bf16 v[86:89], v[150:153], v[188:191], v[86:89]
	v_mfma_f32_16x16x32_bf16 v[82:85], v[164:167], v[188:191], v[82:85]
	v_mfma_f32_16x16x32_bf16 v[70:73], v[150:153], v[200:203], v[70:73]
	v_mfma_f32_16x16x32_bf16 v[66:69], v[164:167], v[200:203], v[66:69]
	s_barrier
	s_setprio 0
	s_mov_b32 m0, s39
	s_or_b32 s62, s60, 0x80
	ds_read_b128 v[168:171], v162 offset:49152
	ds_read_b128 v[172:175], v162 offset:50176
	ds_read_b128 v[176:179], v162 offset:51200
	ds_read_b128 v[180:183], v162 offset:52224
	ds_read_b128 v[184:187], v162 offset:53248
	ds_read_b128 v[188:191], v162 offset:54272
	ds_read_b128 v[192:195], v162 offset:55296
	ds_read_b128 v[200:203], v162 offset:56320
	buffer_load_dwordx4 v158, s[16:19], s62 offen lds
	s_mov_b32 m0, s40
	s_add_i32 s60, s60, 0x40080
	buffer_load_dwordx4 v160, s[16:19], s62 offen lds
	s_mov_b32 m0, s43
	s_nop 0
	buffer_load_dwordx4 v158, s[16:19], s60 offen lds
	s_mov_b32 m0, s42
	s_nop 0
	buffer_load_dwordx4 v160, s[16:19], s60 offen lds
	s_add_i32 s59, s59, 2
	s_addk_i32 s2, 0x100
	s_addk_i32 s3, 0x100
	s_cmp_gt_u32 s59, 13
	s_waitcnt vmcnt(6)
	s_waitcnt lgkmcnt(0)
	s_setprio 1
	s_barrier
	v_mfma_f32_16x16x32_bf16 v[62:65], v[130:133], v[168:171], v[62:65]
	v_mfma_f32_16x16x32_bf16 v[58:61], v[138:141], v[168:171], v[58:61]
	v_mfma_f32_16x16x32_bf16 v[46:49], v[130:133], v[176:179], v[46:49]
	v_mfma_f32_16x16x32_bf16 v[42:45], v[138:141], v[176:179], v[42:45]
	v_mfma_f32_16x16x32_bf16 v[30:33], v[130:133], v[184:187], v[30:33]
	v_mfma_f32_16x16x32_bf16 v[26:29], v[138:141], v[184:187], v[26:29]
	v_mfma_f32_16x16x32_bf16 v[14:17], v[130:133], v[192:195], v[14:17]
	v_mfma_f32_16x16x32_bf16 v[10:13], v[138:141], v[192:195], v[10:13]
	v_mfma_f32_16x16x32_bf16 v[62:65], v[134:137], v[172:175], v[62:65]
	v_mfma_f32_16x16x32_bf16 v[58:61], v[142:145], v[172:175], v[58:61]
	v_mfma_f32_16x16x32_bf16 v[46:49], v[134:137], v[180:183], v[46:49]
	v_mfma_f32_16x16x32_bf16 v[42:45], v[142:145], v[180:183], v[42:45]
	v_mfma_f32_16x16x32_bf16 v[30:33], v[134:137], v[188:191], v[30:33]
	v_mfma_f32_16x16x32_bf16 v[26:29], v[142:145], v[188:191], v[26:29]
	v_mfma_f32_16x16x32_bf16 v[14:17], v[134:137], v[200:203], v[14:17]
	v_mfma_f32_16x16x32_bf16 v[10:13], v[142:145], v[200:203], v[10:13]
	v_mfma_f32_16x16x32_bf16 v[54:57], v[146:149], v[168:171], v[54:57]
	v_mfma_f32_16x16x32_bf16 v[50:53], v[154:157], v[168:171], v[50:53]
	v_mfma_f32_16x16x32_bf16 v[38:41], v[146:149], v[176:179], v[38:41]
	v_mfma_f32_16x16x32_bf16 v[34:37], v[154:157], v[176:179], v[34:37]
	v_mfma_f32_16x16x32_bf16 v[22:25], v[146:149], v[184:187], v[22:25]
	v_mfma_f32_16x16x32_bf16 v[18:21], v[154:157], v[184:187], v[18:21]
	v_mfma_f32_16x16x32_bf16 v[6:9], v[146:149], v[192:195], v[6:9]
	v_mfma_f32_16x16x32_bf16 v[2:5], v[154:157], v[192:195], v[2:5]
	v_mfma_f32_16x16x32_bf16 v[54:57], v[150:153], v[172:175], v[54:57]
	v_mfma_f32_16x16x32_bf16 v[50:53], v[164:167], v[172:175], v[50:53]
	v_mfma_f32_16x16x32_bf16 v[38:41], v[150:153], v[180:183], v[38:41]
	v_mfma_f32_16x16x32_bf16 v[34:37], v[164:167], v[180:183], v[34:37]
	v_mfma_f32_16x16x32_bf16 v[22:25], v[150:153], v[188:191], v[22:25]
	v_mfma_f32_16x16x32_bf16 v[18:21], v[164:167], v[188:191], v[18:21]
	v_mfma_f32_16x16x32_bf16 v[6:9], v[150:153], v[200:203], v[6:9]
	v_mfma_f32_16x16x32_bf16 v[2:5], v[164:167], v[200:203], v[2:5]
	s_barrier
	s_setprio 0
	s_cbranch_scc0 .LBB0_1235
	s_mov_b32 m0, s41
	s_nop 0
	buffer_load_dwordx4 v0, s[20:23], s61 offen lds
	s_mov_b32 m0, s33
	s_nop 0
	buffer_load_dwordx4 v159, s[20:23], s61 offen lds
	v_readlane_b32 s2, v251, 45
	v_readlane_b32 s3, v251, 46
	s_and_b64 vcc, exec, s[2:3]
	s_cbranch_vccz .LBB0_1238
	s_barrier

.LBB0_1461:
	s_add_i32 s100, s55, 0xfffc0000
	v_add_u32_e32 v138, 0x10000, v136
	v_add_u32_e32 v139, 0x14000, v136
	ds_read_b128 v[140:143], v138
	ds_read_b128 v[144:147], v138 offset:1024
	ds_read_b128 v[148:151], v138 offset:2048
	ds_read_b128 v[152:155], v138 offset:3072
	ds_read_b128 v[156:159], v139
	ds_read_b128 v[160:163], v139 offset:1024
	ds_read_b128 v[164:167], v139 offset:2048
	ds_read_b128 v[168:171], v139 offset:3072
	s_mov_b32 m0, s41
	s_nop 0
	buffer_load_dwordx4 v132, s[12:15], s100 offen lds
	s_mov_b32 m0, s33
	s_nop 0
	buffer_load_dwordx4 v134, s[12:15], s100 offen lds
	s_mov_b32 m0, s45
	ds_read_b128 v[172:175], v137
	ds_read_b128 v[176:179], v137 offset:1024
	ds_read_b128 v[180:183], v137 offset:2048
	ds_read_b128 v[184:187], v137 offset:3072
	ds_read_b128 v[188:191], v137 offset:4096
	ds_read_b128 v[192:195], v137 offset:5120
	ds_read_b128 v[200:203], v137 offset:6144
	ds_read_b128 v[204:207], v137 offset:7168
	buffer_load_dwordx4 v132, s[12:15], s55 offen lds
	s_mov_b32 m0, s46
	s_nop 0
	buffer_load_dwordx4 v134, s[12:15], s55 offen lds
	s_waitcnt vmcnt(8)
	s_waitcnt lgkmcnt(0)
	s_setprio 1
	s_barrier
	v_mfma_f32_16x16x32_bf16 v[124:127], v[140:143], v[172:175], v[124:127]
	v_mfma_f32_16x16x32_bf16 v[116:119], v[148:151], v[172:175], v[116:119]
	v_mfma_f32_16x16x32_bf16 v[108:111], v[140:143], v[180:183], v[108:111]
	v_mfma_f32_16x16x32_bf16 v[100:103], v[148:151], v[180:183], v[100:103]
	v_mfma_f32_16x16x32_bf16 v[92:95], v[140:143], v[188:191], v[92:95]
	v_mfma_f32_16x16x32_bf16 v[84:87], v[148:151], v[188:191], v[84:87]
	v_mfma_f32_16x16x32_bf16 v[76:79], v[140:143], v[200:203], v[76:79]
	v_mfma_f32_16x16x32_bf16 v[64:67], v[148:151], v[200:203], v[64:67]
	v_mfma_f32_16x16x32_bf16 v[124:127], v[144:147], v[176:179], v[124:127]
	v_mfma_f32_16x16x32_bf16 v[116:119], v[152:155], v[176:179], v[116:119]
	v_mfma_f32_16x16x32_bf16 v[108:111], v[144:147], v[184:187], v[108:111]
	v_mfma_f32_16x16x32_bf16 v[100:103], v[152:155], v[184:187], v[100:103]
	v_mfma_f32_16x16x32_bf16 v[92:95], v[144:147], v[192:195], v[92:95]
	v_mfma_f32_16x16x32_bf16 v[84:87], v[152:155], v[192:195], v[84:87]
	v_mfma_f32_16x16x32_bf16 v[76:79], v[144:147], v[204:207], v[76:79]
	v_mfma_f32_16x16x32_bf16 v[64:67], v[152:155], v[204:207], v[64:67]
	v_mfma_f32_16x16x32_bf16 v[128:131], v[156:159], v[172:175], v[128:131]
	v_mfma_f32_16x16x32_bf16 v[120:123], v[164:167], v[172:175], v[120:123]
	v_mfma_f32_16x16x32_bf16 v[112:115], v[156:159], v[180:183], v[112:115]
	v_mfma_f32_16x16x32_bf16 v[104:107], v[164:167], v[180:183], v[104:107]
	v_mfma_f32_16x16x32_bf16 v[96:99], v[156:159], v[188:191], v[96:99]
	v_mfma_f32_16x16x32_bf16 v[88:91], v[164:167], v[188:191], v[88:91]
	v_mfma_f32_16x16x32_bf16 v[80:83], v[156:159], v[200:203], v[80:83]
	v_mfma_f32_16x16x32_bf16 v[68:71], v[164:167], v[200:203], v[68:71]
	v_mfma_f32_16x16x32_bf16 v[128:131], v[160:163], v[176:179], v[128:131]
	v_mfma_f32_16x16x32_bf16 v[120:123], v[168:171], v[176:179], v[120:123]
	v_mfma_f32_16x16x32_bf16 v[112:115], v[160:163], v[184:187], v[112:115]
	v_mfma_f32_16x16x32_bf16 v[104:107], v[168:171], v[184:187], v[104:107]
	v_mfma_f32_16x16x32_bf16 v[96:99], v[160:163], v[192:195], v[96:99]
	v_mfma_f32_16x16x32_bf16 v[88:91], v[168:171], v[192:195], v[88:91]
	v_mfma_f32_16x16x32_bf16 v[80:83], v[160:163], v[204:207], v[80:83]
	v_mfma_f32_16x16x32_bf16 v[68:71], v[168:171], v[204:207], v[68:71]
	s_barrier
	s_setprio 0
	s_add_i32 s16, s55, 0xfffc0080
	s_cmp_eq_u32 s54, 12
	s_cselect_b32 s59, s50, s16
	s_cselect_b32 s17, s9, s77
	s_cselect_b32 s16, s8, s76
	s_cselect_b32 s19, s11, s29
	s_cselect_b32 s18, s10, s28
	s_cselect_b32 s57, s51, s56
	s_cselect_b32 s20, s4, s12
	s_cselect_b32 s21, s5, s13
	s_cselect_b32 s22, s6, s14
	s_cselect_b32 s23, s7, s15
	s_or_b32 s58, s59, 0x80
	s_mov_b32 m0, s92
	ds_read_b128 v[172:175], v137 offset:16384
	ds_read_b128 v[176:179], v137 offset:17408
	ds_read_b128 v[180:183], v137 offset:18432
	ds_read_b128 v[184:187], v137 offset:19456
	ds_read_b128 v[188:191], v137 offset:20480
	ds_read_b128 v[192:195], v137 offset:21504
	ds_read_b128 v[200:203], v137 offset:22528
	ds_read_b128 v[204:207], v137 offset:23552
	buffer_load_dwordx4 v133, s[16:19], s57 offen lds
	s_mov_b32 m0, s93
	s_add_i32 s60, s57, 0x40000
	buffer_load_dwordx4 v135, s[16:19], s57 offen lds
	s_mov_b32 m0, s94
	s_nop 0
	buffer_load_dwordx4 v133, s[16:19], s60 offen lds
	s_mov_b32 m0, s95
	s_nop 0
	buffer_load_dwordx4 v135, s[16:19], s60 offen lds
	s_waitcnt vmcnt(6)
	s_waitcnt lgkmcnt(0)
	s_setprio 1
	s_barrier
	v_mfma_f32_16x16x32_bf16 v[60:63], v[140:143], v[172:175], v[60:63]
	v_mfma_f32_16x16x32_bf16 v[52:55], v[148:151], v[172:175], v[52:55]
	v_mfma_f32_16x16x32_bf16 v[44:47], v[140:143], v[180:183], v[44:47]
	v_mfma_f32_16x16x32_bf16 v[36:39], v[148:151], v[180:183], v[36:39]
	v_mfma_f32_16x16x32_bf16 v[28:31], v[140:143], v[188:191], v[28:31]
	v_mfma_f32_16x16x32_bf16 v[20:23], v[148:151], v[188:191], v[20:23]
	v_mfma_f32_16x16x32_bf16 v[12:15], v[140:143], v[200:203], v[12:15]
	v_mfma_f32_16x16x32_bf16 v[2:5], v[148:151], v[200:203], v[4:7]
	v_mfma_f32_16x16x32_bf16 v[60:63], v[144:147], v[176:179], v[60:63]
	v_mfma_f32_16x16x32_bf16 v[52:55], v[152:155], v[176:179], v[52:55]
	v_mfma_f32_16x16x32_bf16 v[44:47], v[144:147], v[184:187], v[44:47]
	v_mfma_f32_16x16x32_bf16 v[36:39], v[152:155], v[184:187], v[36:39]
	v_mfma_f32_16x16x32_bf16 v[28:31], v[144:147], v[192:195], v[28:31]
	v_mfma_f32_16x16x32_bf16 v[20:23], v[152:155], v[192:195], v[20:23]
	v_mfma_f32_16x16x32_bf16 v[12:15], v[144:147], v[204:207], v[12:15]
	v_mfma_f32_16x16x32_bf16 v[2:5], v[152:155], v[204:207], v[2:5]
	v_mfma_f32_16x16x32_bf16 v[72:75], v[156:159], v[172:175], v[72:75]
	v_mfma_f32_16x16x32_bf16 v[56:59], v[164:167], v[172:175], v[56:59]
	v_mfma_f32_16x16x32_bf16 v[48:51], v[156:159], v[180:183], v[48:51]
	v_mfma_f32_16x16x32_bf16 v[40:43], v[164:167], v[180:183], v[40:43]
	v_mfma_f32_16x16x32_bf16 v[32:35], v[156:159], v[188:191], v[32:35]
	v_mfma_f32_16x16x32_bf16 v[24:27], v[164:167], v[188:191], v[24:27]
	v_mfma_f32_16x16x32_bf16 v[16:19], v[156:159], v[200:203], v[16:19]
	v_mfma_f32_16x16x32_bf16 v[6:9], v[164:167], v[200:203], v[8:11]
	v_mfma_f32_16x16x32_bf16 v[72:75], v[160:163], v[176:179], v[72:75]
	v_mfma_f32_16x16x32_bf16 v[56:59], v[168:171], v[176:179], v[56:59]
	v_mfma_f32_16x16x32_bf16 v[48:51], v[160:163], v[184:187], v[48:51]
	v_mfma_f32_16x16x32_bf16 v[40:43], v[168:171], v[184:187], v[40:43]
	v_mfma_f32_16x16x32_bf16 v[32:35], v[160:163], v[192:195], v[32:35]
	v_mfma_f32_16x16x32_bf16 v[24:27], v[168:171], v[192:195], v[24:27]
	v_mfma_f32_16x16x32_bf16 v[16:19], v[160:163], v[204:207], v[16:19]
	v_mfma_f32_16x16x32_bf16 v[8:11], v[168:171], v[204:207], v[6:9]
	s_barrier
	s_setprio 0
	s_mov_b32 m0, s44
	s_nop 0
	buffer_load_dwordx4 v132, s[20:23], s59 offen lds
	s_mov_b32 m0, s36
	s_nop 0
	buffer_load_dwordx4 v134, s[20:23], s59 offen lds
	v_add_u32_e32 v140, 0x18000, v136
	v_add_u32_e32 v141, 0x1c000, v136
	ds_read_b128 v[142:145], v140
	ds_read_b128 v[146:149], v140 offset:1024
	ds_read_b128 v[150:153], v140 offset:2048
	ds_read_b128 v[154:157], v140 offset:3072
	ds_read_b128 v[158:161], v141
	ds_read_b128 v[162:165], v141 offset:1024
	ds_read_b128 v[166:169], v141 offset:2048
	ds_read_b128 v[170:173], v141 offset:3072
	s_add_i32 s59, s59, 0x40000
	s_mov_b32 m0, s37
	ds_read_b128 v[174:177], v137 offset:32768
	ds_read_b128 v[178:181], v137 offset:33792
	ds_read_b128 v[182:185], v137 offset:34816
	ds_read_b128 v[186:189], v137 offset:35840
	ds_read_b128 v[190:193], v137 offset:36864
	ds_read_b128 v[194:197], v137 offset:37888
	ds_read_b128 v[200:203], v137 offset:38912
	ds_read_b128 v[204:207], v137 offset:39936
	buffer_load_dwordx4 v132, s[20:23], s59 offen lds
	s_mov_b32 m0, s38
	s_nop 0
	buffer_load_dwordx4 v134, s[20:23], s59 offen lds
	s_waitcnt vmcnt(8)
	s_waitcnt lgkmcnt(0)
	s_setprio 1
	s_barrier
	v_mfma_f32_16x16x32_bf16 v[124:127], v[142:145], v[174:177], v[124:127]
	v_mfma_f32_16x16x32_bf16 v[116:119], v[150:153], v[174:177], v[116:119]
	v_mfma_f32_16x16x32_bf16 v[108:111], v[142:145], v[182:185], v[108:111]
	v_mfma_f32_16x16x32_bf16 v[100:103], v[150:153], v[182:185], v[100:103]
	v_mfma_f32_16x16x32_bf16 v[92:95], v[142:145], v[190:193], v[92:95]
	v_mfma_f32_16x16x32_bf16 v[84:87], v[150:153], v[190:193], v[84:87]
	v_mfma_f32_16x16x32_bf16 v[76:79], v[142:145], v[200:203], v[76:79]
	v_mfma_f32_16x16x32_bf16 v[64:67], v[150:153], v[200:203], v[64:67]
	v_mfma_f32_16x16x32_bf16 v[124:127], v[146:149], v[178:181], v[124:127]
	v_mfma_f32_16x16x32_bf16 v[116:119], v[154:157], v[178:181], v[116:119]
	v_mfma_f32_16x16x32_bf16 v[108:111], v[146:149], v[186:189], v[108:111]
	v_mfma_f32_16x16x32_bf16 v[100:103], v[154:157], v[186:189], v[100:103]
	v_mfma_f32_16x16x32_bf16 v[92:95], v[146:149], v[194:197], v[92:95]
	v_mfma_f32_16x16x32_bf16 v[84:87], v[154:157], v[194:197], v[84:87]
	v_mfma_f32_16x16x32_bf16 v[76:79], v[146:149], v[204:207], v[76:79]
	v_mfma_f32_16x16x32_bf16 v[64:67], v[154:157], v[204:207], v[64:67]
	v_mfma_f32_16x16x32_bf16 v[128:131], v[158:161], v[174:177], v[128:131]
	v_mfma_f32_16x16x32_bf16 v[120:123], v[166:169], v[174:177], v[120:123]
	v_mfma_f32_16x16x32_bf16 v[112:115], v[158:161], v[182:185], v[112:115]
	v_mfma_f32_16x16x32_bf16 v[104:107], v[166:169], v[182:185], v[104:107]
	v_mfma_f32_16x16x32_bf16 v[96:99], v[158:161], v[190:193], v[96:99]
	v_mfma_f32_16x16x32_bf16 v[88:91], v[166:169], v[190:193], v[88:91]
	v_mfma_f32_16x16x32_bf16 v[80:83], v[158:161], v[200:203], v[80:83]
	v_mfma_f32_16x16x32_bf16 v[68:71], v[166:169], v[200:203], v[68:71]
	v_mfma_f32_16x16x32_bf16 v[128:131], v[162:165], v[178:181], v[128:131]
	v_mfma_f32_16x16x32_bf16 v[120:123], v[170:173], v[178:181], v[120:123]
	v_mfma_f32_16x16x32_bf16 v[112:115], v[162:165], v[186:189], v[112:115]
	v_mfma_f32_16x16x32_bf16 v[104:107], v[170:173], v[186:189], v[104:107]
	v_mfma_f32_16x16x32_bf16 v[96:99], v[162:165], v[194:197], v[96:99]
	v_mfma_f32_16x16x32_bf16 v[88:91], v[170:173], v[194:197], v[88:91]
	v_mfma_f32_16x16x32_bf16 v[80:83], v[162:165], v[204:207], v[80:83]
	v_mfma_f32_16x16x32_bf16 v[68:71], v[170:173], v[204:207], v[68:71]
	s_barrier
	s_setprio 0
	s_mov_b32 m0, s39
	s_or_b32 s59, s57, 0x80
	ds_read_b128 v[174:177], v137 offset:49152
	ds_read_b128 v[178:181], v137 offset:50176
	ds_read_b128 v[182:185], v137 offset:51200
	ds_read_b128 v[186:189], v137 offset:52224
	ds_read_b128 v[190:193], v137 offset:53248
	ds_read_b128 v[194:197], v137 offset:54272
	ds_read_b128 v[200:203], v137 offset:55296
	ds_read_b128 v[204:207], v137 offset:56320
	buffer_load_dwordx4 v133, s[16:19], s59 offen lds
	s_mov_b32 m0, s40
	s_add_i32 s57, s57, 0x40080
	buffer_load_dwordx4 v135, s[16:19], s59 offen lds
	s_mov_b32 m0, s43
	s_nop 0
	buffer_load_dwordx4 v133, s[16:19], s57 offen lds
	s_mov_b32 m0, s42
	s_nop 0
	buffer_load_dwordx4 v135, s[16:19], s57 offen lds
	s_add_i32 s54, s54, 2
	s_addk_i32 s55, 0x100
	s_addk_i32 s56, 0x100
	s_cmp_gt_u32 s54, 13
	s_waitcnt vmcnt(6)
	s_waitcnt lgkmcnt(0)
	s_setprio 1
	s_barrier
	v_mfma_f32_16x16x32_bf16 v[60:63], v[142:145], v[174:177], v[60:63]
	v_mfma_f32_16x16x32_bf16 v[52:55], v[150:153], v[174:177], v[52:55]
	v_mfma_f32_16x16x32_bf16 v[44:47], v[142:145], v[182:185], v[44:47]
	v_mfma_f32_16x16x32_bf16 v[36:39], v[150:153], v[182:185], v[36:39]
	v_mfma_f32_16x16x32_bf16 v[28:31], v[142:145], v[190:193], v[28:31]
	v_mfma_f32_16x16x32_bf16 v[20:23], v[150:153], v[190:193], v[20:23]
	v_mfma_f32_16x16x32_bf16 v[12:15], v[142:145], v[200:203], v[12:15]
	v_mfma_f32_16x16x32_bf16 v[2:5], v[150:153], v[200:203], v[2:5]
	v_mfma_f32_16x16x32_bf16 v[60:63], v[146:149], v[178:181], v[60:63]
	v_mfma_f32_16x16x32_bf16 v[52:55], v[154:157], v[178:181], v[52:55]
	v_mfma_f32_16x16x32_bf16 v[44:47], v[146:149], v[186:189], v[44:47]
	v_mfma_f32_16x16x32_bf16 v[36:39], v[154:157], v[186:189], v[36:39]
	v_mfma_f32_16x16x32_bf16 v[28:31], v[146:149], v[194:197], v[28:31]
	v_mfma_f32_16x16x32_bf16 v[20:23], v[154:157], v[194:197], v[20:23]
	v_mfma_f32_16x16x32_bf16 v[12:15], v[146:149], v[204:207], v[12:15]
	v_mfma_f32_16x16x32_bf16 v[4:7], v[154:157], v[204:207], v[2:5]
	v_mfma_f32_16x16x32_bf16 v[72:75], v[158:161], v[174:177], v[72:75]
	v_mfma_f32_16x16x32_bf16 v[56:59], v[166:169], v[174:177], v[56:59]
	v_mfma_f32_16x16x32_bf16 v[48:51], v[158:161], v[182:185], v[48:51]
	v_mfma_f32_16x16x32_bf16 v[40:43], v[166:169], v[182:185], v[40:43]
	v_mfma_f32_16x16x32_bf16 v[32:35], v[158:161], v[190:193], v[32:35]
	v_mfma_f32_16x16x32_bf16 v[24:27], v[166:169], v[190:193], v[24:27]
	v_mfma_f32_16x16x32_bf16 v[16:19], v[158:161], v[200:203], v[16:19]
	v_mfma_f32_16x16x32_bf16 v[8:11], v[166:169], v[200:203], v[8:11]
	v_mfma_f32_16x16x32_bf16 v[72:75], v[162:165], v[178:181], v[72:75]
	v_mfma_f32_16x16x32_bf16 v[56:59], v[170:173], v[178:181], v[56:59]
	v_mfma_f32_16x16x32_bf16 v[48:51], v[162:165], v[186:189], v[48:51]
	v_mfma_f32_16x16x32_bf16 v[40:43], v[170:173], v[186:189], v[40:43]
	v_mfma_f32_16x16x32_bf16 v[32:35], v[162:165], v[194:197], v[32:35]
	v_mfma_f32_16x16x32_bf16 v[24:27], v[170:173], v[194:197], v[24:27]
	v_mfma_f32_16x16x32_bf16 v[16:19], v[162:165], v[204:207], v[16:19]
	v_mfma_f32_16x16x32_bf16 v[8:11], v[170:173], v[204:207], v[8:11]
	s_barrier
	s_setprio 0
	s_cbranch_scc0 .LBB0_1461
	s_mov_b32 m0, s41
	s_nop 0
	buffer_load_dwordx4 v132, s[20:23], s58 offen lds
	s_mov_b32 m0, s33
	s_nop 0
	buffer_load_dwordx4 v134, s[20:23], s58 offen lds
	v_readlane_b32 s12, v251, 45
	v_readlane_b32 s13, v251, 46
	s_and_b64 vcc, exec, s[12:13]
	s_cbranch_vccz .LBB0_1464
	s_barrier

; #define PG8_WAIT_V(n) asm volatile("s_waitcnt vmcnt(" #n ")" ::: "memory")
; template <class Epi, bool ALIGN_EPI, bool SP2, class Hook>
; __device__ __forceinline__ void gemm_phase(LAS unsigned char* lds, const Gemm g, const StaticOrder& S, const Epi& E, Acc& acc, const bool fresh, const Hook& H, const int wave_id) {
;     ...
;         for (int t = t0; t < nt; t += 2) {
;             const bool last = (t == nt - 2);
;             const Src a1 = cA + (size_t)(t + 1) * kstep;
;             const Src a2 = last ? nA : cA + (size_t)(t + 2) * kstep, b2 = last ? nB : cB + (size_t)(t + 2) * kstep;
;             const Src a3 = a2 + kstep, b3 = b2 + kstep;
;             if (last && has_next) H(nxt);
;             if constexpr (SP2) {
;             PG8_TRIP_SP2(PG8_WAIT_V(8));
.LBB0_1572:
	s_add_i32 s100, s2, 0xfff40000
	v_add_u32_e32 v142, 0x10000, v161
	v_add_u32_e32 v163, 0x14000, v161
	ds_read_b128 v[130:133], v142
	ds_read_b128 v[134:137], v142 offset:1024
	ds_read_b128 v[138:141], v142 offset:2048
	ds_read_b128 v[142:145], v142 offset:3072
	ds_read_b128 v[146:149], v163
	ds_read_b128 v[150:153], v163 offset:1024
	ds_read_b128 v[154:157], v163 offset:2048
	ds_read_b128 v[164:167], v163 offset:3072
	s_mov_b32 m0, s41
	s_nop 0
	buffer_load_dwordx4 v0, s[12:15], s100 offen lds
	s_mov_b32 m0, s33
	s_nop 0
	buffer_load_dwordx4 v159, s[12:15], s100 offen lds
	s_mov_b32 m0, s45
	ds_read_b128 v[168:171], v162
	ds_read_b128 v[172:175], v162 offset:1024
	ds_read_b128 v[176:179], v162 offset:2048
	ds_read_b128 v[180:183], v162 offset:3072
	ds_read_b128 v[184:187], v162 offset:4096
	ds_read_b128 v[188:191], v162 offset:5120
	ds_read_b128 v[192:195], v162 offset:6144
	ds_read_b128 v[200:203], v162 offset:7168
	buffer_load_dwordx4 v0, s[12:15], s2 offen lds
	s_mov_b32 m0, s46
	s_nop 0
	buffer_load_dwordx4 v159, s[12:15], s2 offen lds
	s_waitcnt vmcnt(8)
	s_waitcnt lgkmcnt(0)
	s_setprio 1
	s_barrier
	v_mfma_f32_16x16x32_bf16 v[126:129], v[130:133], v[168:171], v[126:129]
	v_mfma_f32_16x16x32_bf16 v[122:125], v[138:141], v[168:171], v[122:125]
	v_mfma_f32_16x16x32_bf16 v[110:113], v[130:133], v[176:179], v[110:113]
	v_mfma_f32_16x16x32_bf16 v[106:109], v[138:141], v[176:179], v[106:109]
	v_mfma_f32_16x16x32_bf16 v[94:97], v[130:133], v[184:187], v[94:97]
	v_mfma_f32_16x16x32_bf16 v[90:93], v[138:141], v[184:187], v[90:93]
	v_mfma_f32_16x16x32_bf16 v[78:81], v[130:133], v[192:195], v[78:81]
	v_mfma_f32_16x16x32_bf16 v[74:77], v[138:141], v[192:195], v[74:77]
	v_mfma_f32_16x16x32_bf16 v[126:129], v[134:137], v[172:175], v[126:129]
	v_mfma_f32_16x16x32_bf16 v[122:125], v[142:145], v[172:175], v[122:125]
	v_mfma_f32_16x16x32_bf16 v[110:113], v[134:137], v[180:183], v[110:113]
	v_mfma_f32_16x16x32_bf16 v[106:109], v[142:145], v[180:183], v[106:109]
	v_mfma_f32_16x16x32_bf16 v[94:97], v[134:137], v[188:191], v[94:97]
	v_mfma_f32_16x16x32_bf16 v[90:93], v[142:145], v[188:191], v[90:93]
	v_mfma_f32_16x16x32_bf16 v[78:81], v[134:137], v[200:203], v[78:81]
	v_mfma_f32_16x16x32_bf16 v[74:77], v[142:145], v[200:203], v[74:77]
	v_mfma_f32_16x16x32_bf16 v[118:121], v[146:149], v[168:171], v[118:121]
	v_mfma_f32_16x16x32_bf16 v[114:117], v[154:157], v[168:171], v[114:117]
	v_mfma_f32_16x16x32_bf16 v[102:105], v[146:149], v[176:179], v[102:105]
	v_mfma_f32_16x16x32_bf16 v[98:101], v[154:157], v[176:179], v[98:101]
	v_mfma_f32_16x16x32_bf16 v[86:89], v[146:149], v[184:187], v[86:89]
	v_mfma_f32_16x16x32_bf16 v[82:85], v[154:157], v[184:187], v[82:85]
	v_mfma_f32_16x16x32_bf16 v[70:73], v[146:149], v[192:195], v[70:73]
	v_mfma_f32_16x16x32_bf16 v[66:69], v[154:157], v[192:195], v[66:69]
	v_mfma_f32_16x16x32_bf16 v[118:121], v[150:153], v[172:175], v[118:121]
	v_mfma_f32_16x16x32_bf16 v[114:117], v[164:167], v[172:175], v[114:117]
	v_mfma_f32_16x16x32_bf16 v[102:105], v[150:153], v[180:183], v[102:105]
	v_mfma_f32_16x16x32_bf16 v[98:101], v[164:167], v[180:183], v[98:101]
	v_mfma_f32_16x16x32_bf16 v[86:89], v[150:153], v[188:191], v[86:89]
	v_mfma_f32_16x16x32_bf16 v[82:85], v[164:167], v[188:191], v[82:85]
	v_mfma_f32_16x16x32_bf16 v[70:73], v[150:153], v[200:203], v[70:73]
	v_mfma_f32_16x16x32_bf16 v[66:69], v[164:167], v[200:203], v[66:69]
	s_barrier
	s_setprio 0
	s_add_i32 s16, s2, 0xfff40080
	s_cmp_eq_u32 s61, 40
	s_cselect_b32 s64, s57, s16
	s_cselect_b32 s17, s35, s9
	s_cselect_b32 s16, s34, s8
	s_cselect_b32 s19, s51, s53
	s_cselect_b32 s18, s50, s52
	s_cselect_b32 s62, s58, s3
	s_cselect_b32 s20, s10, s12
	s_cselect_b32 s21, s11, s13
	s_cselect_b32 s22, s30, s14
	s_cselect_b32 s23, s31, s15
	s_or_b32 s63, s64, 0x80
	s_mov_b32 m0, s92
	ds_read_b128 v[168:171], v162 offset:16384
	ds_read_b128 v[172:175], v162 offset:17408
	ds_read_b128 v[176:179], v162 offset:18432
	ds_read_b128 v[180:183], v162 offset:19456
	ds_read_b128 v[184:187], v162 offset:20480
	ds_read_b128 v[188:191], v162 offset:21504
	ds_read_b128 v[192:195], v162 offset:22528
	ds_read_b128 v[200:203], v162 offset:23552
	buffer_load_dwordx4 v158, s[16:19], s62 offen lds
	s_mov_b32 m0, s93
	s_add_i32 s65, s62, 0xb0000
	buffer_load_dwordx4 v160, s[16:19], s62 offen lds
	s_mov_b32 m0, s94
	s_nop 0
	buffer_load_dwordx4 v158, s[16:19], s65 offen lds
	s_mov_b32 m0, s95
	s_nop 0
	buffer_load_dwordx4 v160, s[16:19], s65 offen lds
	s_waitcnt vmcnt(6)
	s_waitcnt lgkmcnt(0)
	s_setprio 1
	s_barrier
	v_mfma_f32_16x16x32_bf16 v[62:65], v[130:133], v[168:171], v[62:65]
	v_mfma_f32_16x16x32_bf16 v[58:61], v[138:141], v[168:171], v[58:61]
	v_mfma_f32_16x16x32_bf16 v[46:49], v[130:133], v[176:179], v[46:49]
	v_mfma_f32_16x16x32_bf16 v[42:45], v[138:141], v[176:179], v[42:45]
	v_mfma_f32_16x16x32_bf16 v[30:33], v[130:133], v[184:187], v[30:33]
	v_mfma_f32_16x16x32_bf16 v[26:29], v[138:141], v[184:187], v[26:29]
	v_mfma_f32_16x16x32_bf16 v[14:17], v[130:133], v[192:195], v[14:17]
	v_mfma_f32_16x16x32_bf16 v[10:13], v[138:141], v[192:195], v[10:13]
	v_mfma_f32_16x16x32_bf16 v[62:65], v[134:137], v[172:175], v[62:65]
	v_mfma_f32_16x16x32_bf16 v[58:61], v[142:145], v[172:175], v[58:61]
	v_mfma_f32_16x16x32_bf16 v[46:49], v[134:137], v[180:183], v[46:49]
	v_mfma_f32_16x16x32_bf16 v[42:45], v[142:145], v[180:183], v[42:45]
	v_mfma_f32_16x16x32_bf16 v[30:33], v[134:137], v[188:191], v[30:33]
	v_mfma_f32_16x16x32_bf16 v[26:29], v[142:145], v[188:191], v[26:29]
	v_mfma_f32_16x16x32_bf16 v[14:17], v[134:137], v[200:203], v[14:17]
	v_mfma_f32_16x16x32_bf16 v[10:13], v[142:145], v[200:203], v[10:13]
	v_mfma_f32_16x16x32_bf16 v[54:57], v[146:149], v[168:171], v[54:57]
	v_mfma_f32_16x16x32_bf16 v[50:53], v[154:157], v[168:171], v[50:53]
	v_mfma_f32_16x16x32_bf16 v[38:41], v[146:149], v[176:179], v[38:41]
	v_mfma_f32_16x16x32_bf16 v[34:37], v[154:157], v[176:179], v[34:37]
	v_mfma_f32_16x16x32_bf16 v[22:25], v[146:149], v[184:187], v[22:25]
	v_mfma_f32_16x16x32_bf16 v[18:21], v[154:157], v[184:187], v[18:21]
	v_mfma_f32_16x16x32_bf16 v[6:9], v[146:149], v[192:195], v[6:9]
	v_mfma_f32_16x16x32_bf16 v[2:5], v[154:157], v[192:195], v[2:5]
	v_mfma_f32_16x16x32_bf16 v[54:57], v[150:153], v[172:175], v[54:57]
	v_mfma_f32_16x16x32_bf16 v[50:53], v[164:167], v[172:175], v[50:53]
	v_mfma_f32_16x16x32_bf16 v[38:41], v[150:153], v[180:183], v[38:41]
	v_mfma_f32_16x16x32_bf16 v[34:37], v[164:167], v[180:183], v[34:37]
	v_mfma_f32_16x16x32_bf16 v[22:25], v[150:153], v[188:191], v[22:25]
	v_mfma_f32_16x16x32_bf16 v[18:21], v[164:167], v[188:191], v[18:21]
	v_mfma_f32_16x16x32_bf16 v[6:9], v[150:153], v[200:203], v[6:9]
	v_mfma_f32_16x16x32_bf16 v[2:5], v[164:167], v[200:203], v[2:5]
	s_barrier
	s_setprio 0
	s_mov_b32 m0, s44
	s_nop 0
	buffer_load_dwordx4 v0, s[20:23], s64 offen lds
	s_mov_b32 m0, s36
	s_nop 0
	buffer_load_dwordx4 v159, s[20:23], s64 offen lds
	v_add_u32_e32 v142, 0x18000, v161
	v_add_u32_e32 v163, 0x1c000, v161
	ds_read_b128 v[130:133], v142
	ds_read_b128 v[134:137], v142 offset:1024
	ds_read_b128 v[138:141], v142 offset:2048
	ds_read_b128 v[142:145], v142 offset:3072
	ds_read_b128 v[146:149], v163
	ds_read_b128 v[150:153], v163 offset:1024
	ds_read_b128 v[154:157], v163 offset:2048
	ds_read_b128 v[164:167], v163 offset:3072
	s_add_i32 s64, s64, 0xc0000
	s_mov_b32 m0, s37
	ds_read_b128 v[168:171], v162 offset:32768
	ds_read_b128 v[172:175], v162 offset:33792
	ds_read_b128 v[176:179], v162 offset:34816
	ds_read_b128 v[180:183], v162 offset:35840
	ds_read_b128 v[184:187], v162 offset:36864
	ds_read_b128 v[188:191], v162 offset:37888
	ds_read_b128 v[192:195], v162 offset:38912
	ds_read_b128 v[200:203], v162 offset:39936
	buffer_load_dwordx4 v0, s[20:23], s64 offen lds
	s_mov_b32 m0, s38
	s_nop 0
	buffer_load_dwordx4 v159, s[20:23], s64 offen lds
	s_waitcnt vmcnt(8)
	s_waitcnt lgkmcnt(0)
	s_setprio 1
	s_barrier
	v_mfma_f32_16x16x32_bf16 v[126:129], v[130:133], v[168:171], v[126:129]
	v_mfma_f32_16x16x32_bf16 v[122:125], v[138:141], v[168:171], v[122:125]
	v_mfma_f32_16x16x32_bf16 v[110:113], v[130:133], v[176:179], v[110:113]
	v_mfma_f32_16x16x32_bf16 v[106:109], v[138:141], v[176:179], v[106:109]
	v_mfma_f32_16x16x32_bf16 v[94:97], v[130:133], v[184:187], v[94:97]
	v_mfma_f32_16x16x32_bf16 v[90:93], v[138:141], v[184:187], v[90:93]
	v_mfma_f32_16x16x32_bf16 v[78:81], v[130:133], v[192:195], v[78:81]
	v_mfma_f32_16x16x32_bf16 v[74:77], v[138:141], v[192:195], v[74:77]
	v_mfma_f32_16x16x32_bf16 v[126:129], v[134:137], v[172:175], v[126:129]
	v_mfma_f32_16x16x32_bf16 v[122:125], v[142:145], v[172:175], v[122:125]
	v_mfma_f32_16x16x32_bf16 v[110:113], v[134:137], v[180:183], v[110:113]
	v_mfma_f32_16x16x32_bf16 v[106:109], v[142:145], v[180:183], v[106:109]
	v_mfma_f32_16x16x32_bf16 v[94:97], v[134:137], v[188:191], v[94:97]
	v_mfma_f32_16x16x32_bf16 v[90:93], v[142:145], v[188:191], v[90:93]
	v_mfma_f32_16x16x32_bf16 v[78:81], v[134:137], v[200:203], v[78:81]
	v_mfma_f32_16x16x32_bf16 v[74:77], v[142:145], v[200:203], v[74:77]
	v_mfma_f32_16x16x32_bf16 v[118:121], v[146:149], v[168:171], v[118:121]
	v_mfma_f32_16x16x32_bf16 v[114:117], v[154:157], v[168:171], v[114:117]
	v_mfma_f32_16x16x32_bf16 v[102:105], v[146:149], v[176:179], v[102:105]
	v_mfma_f32_16x16x32_bf16 v[98:101], v[154:157], v[176:179], v[98:101]
	v_mfma_f32_16x16x32_bf16 v[86:89], v[146:149], v[184:187], v[86:89]
	v_mfma_f32_16x16x32_bf16 v[82:85], v[154:157], v[184:187], v[82:85]
	v_mfma_f32_16x16x32_bf16 v[70:73], v[146:149], v[192:195], v[70:73]
	v_mfma_f32_16x16x32_bf16 v[66:69], v[154:157], v[192:195], v[66:69]
	v_mfma_f32_16x16x32_bf16 v[118:121], v[150:153], v[172:175], v[118:121]
	v_mfma_f32_16x16x32_bf16 v[114:117], v[164:167], v[172:175], v[114:117]
	v_mfma_f32_16x16x32_bf16 v[102:105], v[150:153], v[180:183], v[102:105]
	v_mfma_f32_16x16x32_bf16 v[98:101], v[164:167], v[180:183], v[98:101]
	v_mfma_f32_16x16x32_bf16 v[86:89], v[150:153], v[188:191], v[86:89]
	v_mfma_f32_16x16x32_bf16 v[82:85], v[164:167], v[188:191], v[82:85]
	v_mfma_f32_16x16x32_bf16 v[70:73], v[150:153], v[200:203], v[70:73]
	v_mfma_f32_16x16x32_bf16 v[66:69], v[164:167], v[200:203], v[66:69]
	s_barrier
	s_setprio 0
	s_mov_b32 m0, s39
	s_or_b32 s64, s62, 0x80
	ds_read_b128 v[168:171], v162 offset:49152
	ds_read_b128 v[172:175], v162 offset:50176
	ds_read_b128 v[176:179], v162 offset:51200
	ds_read_b128 v[180:183], v162 offset:52224
	ds_read_b128 v[184:187], v162 offset:53248
	ds_read_b128 v[188:191], v162 offset:54272
	ds_read_b128 v[192:195], v162 offset:55296
	ds_read_b128 v[200:203], v162 offset:56320
	buffer_load_dwordx4 v158, s[16:19], s64 offen lds
	s_mov_b32 m0, s40
	s_add_i32 s62, s62, 0xb0080
	buffer_load_dwordx4 v160, s[16:19], s64 offen lds
	s_mov_b32 m0, s43
	s_nop 0
	buffer_load_dwordx4 v158, s[16:19], s62 offen lds
	s_mov_b32 m0, s42
	s_nop 0
	buffer_load_dwordx4 v160, s[16:19], s62 offen lds
	s_add_i32 s61, s61, 2
	s_addk_i32 s2, 0x100
	s_addk_i32 s3, 0x100
	s_cmp_gt_u32 s61, 41
	s_waitcnt vmcnt(6)
	s_waitcnt lgkmcnt(0)
	s_setprio 1
	s_barrier
	v_mfma_f32_16x16x32_bf16 v[62:65], v[130:133], v[168:171], v[62:65]
	v_mfma_f32_16x16x32_bf16 v[58:61], v[138:141], v[168:171], v[58:61]
	v_mfma_f32_16x16x32_bf16 v[46:49], v[130:133], v[176:179], v[46:49]
	v_mfma_f32_16x16x32_bf16 v[42:45], v[138:141], v[176:179], v[42:45]
	v_mfma_f32_16x16x32_bf16 v[30:33], v[130:133], v[184:187], v[30:33]
	v_mfma_f32_16x16x32_bf16 v[26:29], v[138:141], v[184:187], v[26:29]
	v_mfma_f32_16x16x32_bf16 v[14:17], v[130:133], v[192:195], v[14:17]
	v_mfma_f32_16x16x32_bf16 v[10:13], v[138:141], v[192:195], v[10:13]
	v_mfma_f32_16x16x32_bf16 v[62:65], v[134:137], v[172:175], v[62:65]
	v_mfma_f32_16x16x32_bf16 v[58:61], v[142:145], v[172:175], v[58:61]
	v_mfma_f32_16x16x32_bf16 v[46:49], v[134:137], v[180:183], v[46:49]
	v_mfma_f32_16x16x32_bf16 v[42:45], v[142:145], v[180:183], v[42:45]
	v_mfma_f32_16x16x32_bf16 v[30:33], v[134:137], v[188:191], v[30:33]
	v_mfma_f32_16x16x32_bf16 v[26:29], v[142:145], v[188:191], v[26:29]
	v_mfma_f32_16x16x32_bf16 v[14:17], v[134:137], v[200:203], v[14:17]
	v_mfma_f32_16x16x32_bf16 v[10:13], v[142:145], v[200:203], v[10:13]
	v_mfma_f32_16x16x32_bf16 v[54:57], v[146:149], v[168:171], v[54:57]
	v_mfma_f32_16x16x32_bf16 v[50:53], v[154:157], v[168:171], v[50:53]
	v_mfma_f32_16x16x32_bf16 v[38:41], v[146:149], v[176:179], v[38:41]
	v_mfma_f32_16x16x32_bf16 v[34:37], v[154:157], v[176:179], v[34:37]
	v_mfma_f32_16x16x32_bf16 v[22:25], v[146:149], v[184:187], v[22:25]
	v_mfma_f32_16x16x32_bf16 v[18:21], v[154:157], v[184:187], v[18:21]
	v_mfma_f32_16x16x32_bf16 v[6:9], v[146:149], v[192:195], v[6:9]
	v_mfma_f32_16x16x32_bf16 v[2:5], v[154:157], v[192:195], v[2:5]
	v_mfma_f32_16x16x32_bf16 v[54:57], v[150:153], v[172:175], v[54:57]
	v_mfma_f32_16x16x32_bf16 v[50:53], v[164:167], v[172:175], v[50:53]
	v_mfma_f32_16x16x32_bf16 v[38:41], v[150:153], v[180:183], v[38:41]
	v_mfma_f32_16x16x32_bf16 v[34:37], v[164:167], v[180:183], v[34:37]
	v_mfma_f32_16x16x32_bf16 v[22:25], v[150:153], v[188:191], v[22:25]
	v_mfma_f32_16x16x32_bf16 v[18:21], v[164:167], v[188:191], v[18:21]
	v_mfma_f32_16x16x32_bf16 v[6:9], v[150:153], v[200:203], v[6:9]
	v_mfma_f32_16x16x32_bf16 v[2:5], v[164:167], v[200:203], v[2:5]
	s_barrier
	s_setprio 0
	s_cbranch_scc0 .LBB0_1572
	s_mov_b32 m0, s41
	s_nop 0
	buffer_load_dwordx4 v0, s[20:23], s63 offen lds
	s_mov_b32 m0, s33
	s_nop 0
	buffer_load_dwordx4 v159, s[20:23], s63 offen lds
	v_readlane_b32 s2, v251, 45
	v_readlane_b32 s3, v251, 46
	s_and_b64 vcc, exec, s[2:3]
	s_cbranch_vccz .LBB0_1575
	s_barrier

; #define PG8_WAIT_V(n) asm volatile("s_waitcnt vmcnt(" #n ")" ::: "memory")
; template <class Epi, bool ALIGN_EPI, bool SP2, class Hook>
; __device__ __forceinline__ void gemm_phase(LAS unsigned char* lds, const Gemm g, const StaticOrder& S, const Epi& E, Acc& acc, const bool fresh, const Hook& H, const int wave_id) {
;     ...
;         for (int t = t0; t < nt; t += 2) {
;             const bool last = (t == nt - 2);
;             const Src a1 = cA + (size_t)(t + 1) * kstep;
;             const Src a2 = last ? nA : cA + (size_t)(t + 2) * kstep, b2 = last ? nB : cB + (size_t)(t + 2) * kstep;
;             const Src a3 = a2 + kstep, b3 = b2 + kstep;
;             if (last && has_next) H(nxt);
;             if constexpr (SP2) {
;             PG8_TRIP_SP2(PG8_WAIT_V(8));
.LBB0_1614:
	s_add_i32 s100, s2, 0xfff40000
	v_add_u32_e32 v0, 0x10000, v172
	ds_read_b128 v[130:133], v0
	ds_read_b128 v[134:137], v0 offset:1024
	ds_read_b128 v[138:141], v0 offset:2048
	ds_read_b128 v[142:145], v0 offset:3072
	v_add_u32_e32 v0, 0x14000, v172
	ds_read_b128 v[146:149], v0
	ds_read_b128 v[150:153], v0 offset:1024
	ds_read_b128 v[154:157], v0 offset:2048
	ds_read_b128 v[158:161], v0 offset:3072
	s_mov_b32 m0, s41
	s_nop 0
	buffer_load_dwordx4 v168, s[8:11], s100 offen lds
	s_mov_b32 m0, s33
	s_nop 0
	buffer_load_dwordx4 v170, s[8:11], s100 offen lds
	s_mov_b32 m0, s45
	ds_read_b128 v[162:165], v173
	ds_read_b128 v[174:177], v173 offset:1024
	ds_read_b128 v[178:181], v173 offset:2048
	ds_read_b128 v[182:185], v173 offset:3072
	ds_read_b128 v[186:189], v173 offset:4096
	ds_read_b128 v[190:193], v173 offset:5120
	ds_read_b128 v[194:197], v173 offset:6144
	ds_read_b128 v[200:203], v173 offset:7168
	buffer_load_dwordx4 v168, s[8:11], s2 offen lds
	s_mov_b32 m0, s46
	s_nop 0
	buffer_load_dwordx4 v170, s[8:11], s2 offen lds
	s_waitcnt vmcnt(8)
	s_waitcnt lgkmcnt(0)
	s_setprio 1
	s_barrier
	v_mfma_f32_16x16x32_bf16 v[126:129], v[130:133], v[162:165], v[126:129]
	v_mfma_f32_16x16x32_bf16 v[122:125], v[138:141], v[162:165], v[122:125]
	v_mfma_f32_16x16x32_bf16 v[110:113], v[130:133], v[178:181], v[110:113]
	v_mfma_f32_16x16x32_bf16 v[106:109], v[138:141], v[178:181], v[106:109]
	v_mfma_f32_16x16x32_bf16 v[94:97], v[130:133], v[186:189], v[94:97]
	v_mfma_f32_16x16x32_bf16 v[90:93], v[138:141], v[186:189], v[90:93]
	v_mfma_f32_16x16x32_bf16 v[78:81], v[130:133], v[194:197], v[78:81]
	v_mfma_f32_16x16x32_bf16 v[74:77], v[138:141], v[194:197], v[74:77]
	v_mfma_f32_16x16x32_bf16 v[126:129], v[134:137], v[174:177], v[126:129]
	v_mfma_f32_16x16x32_bf16 v[122:125], v[142:145], v[174:177], v[122:125]
	v_mfma_f32_16x16x32_bf16 v[110:113], v[134:137], v[182:185], v[110:113]
	v_mfma_f32_16x16x32_bf16 v[106:109], v[142:145], v[182:185], v[106:109]
	v_mfma_f32_16x16x32_bf16 v[94:97], v[134:137], v[190:193], v[94:97]
	v_mfma_f32_16x16x32_bf16 v[90:93], v[142:145], v[190:193], v[90:93]
	v_mfma_f32_16x16x32_bf16 v[78:81], v[134:137], v[200:203], v[78:81]
	v_mfma_f32_16x16x32_bf16 v[74:77], v[142:145], v[200:203], v[74:77]
	v_mfma_f32_16x16x32_bf16 v[118:121], v[146:149], v[162:165], v[118:121]
	v_mfma_f32_16x16x32_bf16 v[114:117], v[154:157], v[162:165], v[114:117]
	v_mfma_f32_16x16x32_bf16 v[102:105], v[146:149], v[178:181], v[102:105]
	v_mfma_f32_16x16x32_bf16 v[98:101], v[154:157], v[178:181], v[98:101]
	v_mfma_f32_16x16x32_bf16 v[86:89], v[146:149], v[186:189], v[86:89]
	v_mfma_f32_16x16x32_bf16 v[82:85], v[154:157], v[186:189], v[82:85]
	v_mfma_f32_16x16x32_bf16 v[70:73], v[146:149], v[194:197], v[70:73]
	v_mfma_f32_16x16x32_bf16 v[66:69], v[154:157], v[194:197], v[66:69]
	v_mfma_f32_16x16x32_bf16 v[118:121], v[150:153], v[174:177], v[118:121]
	v_mfma_f32_16x16x32_bf16 v[114:117], v[158:161], v[174:177], v[114:117]
	v_mfma_f32_16x16x32_bf16 v[102:105], v[150:153], v[182:185], v[102:105]
	v_mfma_f32_16x16x32_bf16 v[98:101], v[158:161], v[182:185], v[98:101]
	v_mfma_f32_16x16x32_bf16 v[86:89], v[150:153], v[190:193], v[86:89]
	v_mfma_f32_16x16x32_bf16 v[82:85], v[158:161], v[190:193], v[82:85]
	v_mfma_f32_16x16x32_bf16 v[70:73], v[150:153], v[200:203], v[70:73]
	v_mfma_f32_16x16x32_bf16 v[66:69], v[158:161], v[200:203], v[66:69]
	s_barrier
	s_setprio 0
	s_add_i32 s12, s2, 0xfff40080
	s_cmp_eq_u32 s59, 40
	s_cselect_b32 s62, s55, s12
	s_cselect_b32 s13, s31, s77
	s_cselect_b32 s12, s30, s76
	s_cselect_b32 s15, s35, s51
	s_cselect_b32 s14, s34, s50
	s_cselect_b32 s60, s56, s3
	s_cselect_b32 s16, s20, s8
	s_cselect_b32 s17, s21, s9
	s_cselect_b32 s18, s22, s10
	s_cselect_b32 s19, s23, s11
	s_or_b32 s61, s62, 0x80
	s_mov_b32 m0, s92
	ds_read_b128 v[162:165], v173 offset:16384
	ds_read_b128 v[174:177], v173 offset:17408
	ds_read_b128 v[178:181], v173 offset:18432
	ds_read_b128 v[182:185], v173 offset:19456
	ds_read_b128 v[186:189], v173 offset:20480
	ds_read_b128 v[190:193], v173 offset:21504
	ds_read_b128 v[194:197], v173 offset:22528
	ds_read_b128 v[200:203], v173 offset:23552
	buffer_load_dwordx4 v169, s[12:15], s60 offen lds
	s_mov_b32 m0, s93
	s_add_i32 s63, s60, 0xb0000
	buffer_load_dwordx4 v171, s[12:15], s60 offen lds
	s_mov_b32 m0, s94
	s_nop 0
	buffer_load_dwordx4 v169, s[12:15], s63 offen lds
	s_mov_b32 m0, s95
	s_nop 0
	buffer_load_dwordx4 v171, s[12:15], s63 offen lds
	s_waitcnt vmcnt(6)
	s_waitcnt lgkmcnt(0)
	s_setprio 1
	s_barrier
	v_mfma_f32_16x16x32_bf16 v[62:65], v[130:133], v[162:165], v[62:65]
	v_mfma_f32_16x16x32_bf16 v[58:61], v[138:141], v[162:165], v[58:61]
	v_mfma_f32_16x16x32_bf16 v[46:49], v[130:133], v[178:181], v[46:49]
	v_mfma_f32_16x16x32_bf16 v[42:45], v[138:141], v[178:181], v[42:45]
	v_mfma_f32_16x16x32_bf16 v[30:33], v[130:133], v[186:189], v[30:33]
	v_mfma_f32_16x16x32_bf16 v[26:29], v[138:141], v[186:189], v[26:29]
	v_mfma_f32_16x16x32_bf16 v[14:17], v[130:133], v[194:197], v[14:17]
	v_mfma_f32_16x16x32_bf16 v[10:13], v[138:141], v[194:197], v[10:13]
	v_mfma_f32_16x16x32_bf16 v[62:65], v[134:137], v[174:177], v[62:65]
	v_mfma_f32_16x16x32_bf16 v[58:61], v[142:145], v[174:177], v[58:61]
	v_mfma_f32_16x16x32_bf16 v[46:49], v[134:137], v[182:185], v[46:49]
	v_mfma_f32_16x16x32_bf16 v[42:45], v[142:145], v[182:185], v[42:45]
	v_mfma_f32_16x16x32_bf16 v[30:33], v[134:137], v[190:193], v[30:33]
	v_mfma_f32_16x16x32_bf16 v[26:29], v[142:145], v[190:193], v[26:29]
	v_mfma_f32_16x16x32_bf16 v[14:17], v[134:137], v[200:203], v[14:17]
	v_mfma_f32_16x16x32_bf16 v[10:13], v[142:145], v[200:203], v[10:13]
	v_mfma_f32_16x16x32_bf16 v[54:57], v[146:149], v[162:165], v[54:57]
	v_mfma_f32_16x16x32_bf16 v[50:53], v[154:157], v[162:165], v[50:53]
	v_mfma_f32_16x16x32_bf16 v[38:41], v[146:149], v[178:181], v[38:41]
	v_mfma_f32_16x16x32_bf16 v[34:37], v[154:157], v[178:181], v[34:37]
	v_mfma_f32_16x16x32_bf16 v[22:25], v[146:149], v[186:189], v[22:25]
	v_mfma_f32_16x16x32_bf16 v[18:21], v[154:157], v[186:189], v[18:21]
	v_mfma_f32_16x16x32_bf16 v[6:9], v[146:149], v[194:197], v[6:9]
	v_mfma_f32_16x16x32_bf16 v[2:5], v[154:157], v[194:197], v[2:5]
	v_mfma_f32_16x16x32_bf16 v[54:57], v[150:153], v[174:177], v[54:57]
	v_mfma_f32_16x16x32_bf16 v[50:53], v[158:161], v[174:177], v[50:53]
	v_mfma_f32_16x16x32_bf16 v[38:41], v[150:153], v[182:185], v[38:41]
	v_mfma_f32_16x16x32_bf16 v[34:37], v[158:161], v[182:185], v[34:37]
	v_mfma_f32_16x16x32_bf16 v[22:25], v[150:153], v[190:193], v[22:25]
	v_mfma_f32_16x16x32_bf16 v[18:21], v[158:161], v[190:193], v[18:21]
	v_mfma_f32_16x16x32_bf16 v[6:9], v[150:153], v[200:203], v[6:9]
	v_mfma_f32_16x16x32_bf16 v[2:5], v[158:161], v[200:203], v[2:5]
	s_barrier
	s_setprio 0
	s_mov_b32 m0, s44
	s_nop 0
	buffer_load_dwordx4 v168, s[16:19], s62 offen lds
	s_mov_b32 m0, s36
	s_nop 0
	buffer_load_dwordx4 v170, s[16:19], s62 offen lds
	v_add_u32_e32 v0, 0x18000, v172
	ds_read_b128 v[130:133], v0
	ds_read_b128 v[134:137], v0 offset:1024
	ds_read_b128 v[138:141], v0 offset:2048
	ds_read_b128 v[142:145], v0 offset:3072
	v_add_u32_e32 v0, 0x1c000, v172
	ds_read_b128 v[146:149], v0
	ds_read_b128 v[150:153], v0 offset:1024
	ds_read_b128 v[154:157], v0 offset:2048
	ds_read_b128 v[158:161], v0 offset:3072
	s_add_i32 s62, s62, 0xc0000
	s_mov_b32 m0, s37
	ds_read_b128 v[162:165], v173 offset:32768
	ds_read_b128 v[174:177], v173 offset:33792
	ds_read_b128 v[178:181], v173 offset:34816
	ds_read_b128 v[182:185], v173 offset:35840
	ds_read_b128 v[186:189], v173 offset:36864
	ds_read_b128 v[190:193], v173 offset:37888
	ds_read_b128 v[194:197], v173 offset:38912
	ds_read_b128 v[200:203], v173 offset:39936
	buffer_load_dwordx4 v168, s[16:19], s62 offen lds
	s_mov_b32 m0, s38
	s_nop 0
	buffer_load_dwordx4 v170, s[16:19], s62 offen lds
	s_waitcnt vmcnt(8)
	s_waitcnt lgkmcnt(0)
	s_setprio 1
	s_barrier
	v_mfma_f32_16x16x32_bf16 v[126:129], v[130:133], v[162:165], v[126:129]
	v_mfma_f32_16x16x32_bf16 v[122:125], v[138:141], v[162:165], v[122:125]
	v_mfma_f32_16x16x32_bf16 v[110:113], v[130:133], v[178:181], v[110:113]
	v_mfma_f32_16x16x32_bf16 v[106:109], v[138:141], v[178:181], v[106:109]
	v_mfma_f32_16x16x32_bf16 v[94:97], v[130:133], v[186:189], v[94:97]
	v_mfma_f32_16x16x32_bf16 v[90:93], v[138:141], v[186:189], v[90:93]
	v_mfma_f32_16x16x32_bf16 v[78:81], v[130:133], v[194:197], v[78:81]
	v_mfma_f32_16x16x32_bf16 v[74:77], v[138:141], v[194:197], v[74:77]
	v_mfma_f32_16x16x32_bf16 v[126:129], v[134:137], v[174:177], v[126:129]
	v_mfma_f32_16x16x32_bf16 v[122:125], v[142:145], v[174:177], v[122:125]
	v_mfma_f32_16x16x32_bf16 v[110:113], v[134:137], v[182:185], v[110:113]
	v_mfma_f32_16x16x32_bf16 v[106:109], v[142:145], v[182:185], v[106:109]
	v_mfma_f32_16x16x32_bf16 v[94:97], v[134:137], v[190:193], v[94:97]
	v_mfma_f32_16x16x32_bf16 v[90:93], v[142:145], v[190:193], v[90:93]
	v_mfma_f32_16x16x32_bf16 v[78:81], v[134:137], v[200:203], v[78:81]
	v_mfma_f32_16x16x32_bf16 v[74:77], v[142:145], v[200:203], v[74:77]
	v_mfma_f32_16x16x32_bf16 v[118:121], v[146:149], v[162:165], v[118:121]
	v_mfma_f32_16x16x32_bf16 v[114:117], v[154:157], v[162:165], v[114:117]
	v_mfma_f32_16x16x32_bf16 v[102:105], v[146:149], v[178:181], v[102:105]
	v_mfma_f32_16x16x32_bf16 v[98:101], v[154:157], v[178:181], v[98:101]
	v_mfma_f32_16x16x32_bf16 v[86:89], v[146:149], v[186:189], v[86:89]
	v_mfma_f32_16x16x32_bf16 v[82:85], v[154:157], v[186:189], v[82:85]
	v_mfma_f32_16x16x32_bf16 v[70:73], v[146:149], v[194:197], v[70:73]
	v_mfma_f32_16x16x32_bf16 v[66:69], v[154:157], v[194:197], v[66:69]
	v_mfma_f32_16x16x32_bf16 v[118:121], v[150:153], v[174:177], v[118:121]
	v_mfma_f32_16x16x32_bf16 v[114:117], v[158:161], v[174:177], v[114:117]
	v_mfma_f32_16x16x32_bf16 v[102:105], v[150:153], v[182:185], v[102:105]
	v_mfma_f32_16x16x32_bf16 v[98:101], v[158:161], v[182:185], v[98:101]
	v_mfma_f32_16x16x32_bf16 v[86:89], v[150:153], v[190:193], v[86:89]
	v_mfma_f32_16x16x32_bf16 v[82:85], v[158:161], v[190:193], v[82:85]
	v_mfma_f32_16x16x32_bf16 v[70:73], v[150:153], v[200:203], v[70:73]
	v_mfma_f32_16x16x32_bf16 v[66:69], v[158:161], v[200:203], v[66:69]
	s_barrier
	s_setprio 0
	s_mov_b32 m0, s39
	s_or_b32 s62, s60, 0x80
	ds_read_b128 v[162:165], v173 offset:49152
	ds_read_b128 v[174:177], v173 offset:50176
	ds_read_b128 v[178:181], v173 offset:51200
	ds_read_b128 v[182:185], v173 offset:52224
	ds_read_b128 v[186:189], v173 offset:53248
	ds_read_b128 v[190:193], v173 offset:54272
	ds_read_b128 v[194:197], v173 offset:55296
	ds_read_b128 v[200:203], v173 offset:56320
	buffer_load_dwordx4 v169, s[12:15], s62 offen lds
	s_mov_b32 m0, s40
	s_add_i32 s60, s60, 0xb0080
	buffer_load_dwordx4 v171, s[12:15], s62 offen lds
	s_mov_b32 m0, s43
	s_nop 0
	buffer_load_dwordx4 v169, s[12:15], s60 offen lds
	s_mov_b32 m0, s42
	s_nop 0
	buffer_load_dwordx4 v171, s[12:15], s60 offen lds
	s_add_i32 s59, s59, 2
	s_addk_i32 s2, 0x100
	s_addk_i32 s3, 0x100
	s_cmp_gt_u32 s59, 41
	s_waitcnt vmcnt(6)
	s_waitcnt lgkmcnt(0)
	s_setprio 1
	s_barrier
	v_mfma_f32_16x16x32_bf16 v[62:65], v[130:133], v[162:165], v[62:65]
	v_mfma_f32_16x16x32_bf16 v[58:61], v[138:141], v[162:165], v[58:61]
	v_mfma_f32_16x16x32_bf16 v[46:49], v[130:133], v[178:181], v[46:49]
	v_mfma_f32_16x16x32_bf16 v[42:45], v[138:141], v[178:181], v[42:45]
	v_mfma_f32_16x16x32_bf16 v[30:33], v[130:133], v[186:189], v[30:33]
	v_mfma_f32_16x16x32_bf16 v[26:29], v[138:141], v[186:189], v[26:29]
	v_mfma_f32_16x16x32_bf16 v[14:17], v[130:133], v[194:197], v[14:17]
	v_mfma_f32_16x16x32_bf16 v[10:13], v[138:141], v[194:197], v[10:13]
	v_mfma_f32_16x16x32_bf16 v[62:65], v[134:137], v[174:177], v[62:65]
	v_mfma_f32_16x16x32_bf16 v[58:61], v[142:145], v[174:177], v[58:61]
	v_mfma_f32_16x16x32_bf16 v[46:49], v[134:137], v[182:185], v[46:49]
	v_mfma_f32_16x16x32_bf16 v[42:45], v[142:145], v[182:185], v[42:45]
	v_mfma_f32_16x16x32_bf16 v[30:33], v[134:137], v[190:193], v[30:33]
	v_mfma_f32_16x16x32_bf16 v[26:29], v[142:145], v[190:193], v[26:29]
	v_mfma_f32_16x16x32_bf16 v[14:17], v[134:137], v[200:203], v[14:17]
	v_mfma_f32_16x16x32_bf16 v[10:13], v[142:145], v[200:203], v[10:13]
	v_mfma_f32_16x16x32_bf16 v[54:57], v[146:149], v[162:165], v[54:57]
	v_mfma_f32_16x16x32_bf16 v[50:53], v[154:157], v[162:165], v[50:53]
	v_mfma_f32_16x16x32_bf16 v[38:41], v[146:149], v[178:181], v[38:41]
	v_mfma_f32_16x16x32_bf16 v[34:37], v[154:157], v[178:181], v[34:37]
	v_mfma_f32_16x16x32_bf16 v[22:25], v[146:149], v[186:189], v[22:25]
	v_mfma_f32_16x16x32_bf16 v[18:21], v[154:157], v[186:189], v[18:21]
	v_mfma_f32_16x16x32_bf16 v[6:9], v[146:149], v[194:197], v[6:9]
	v_mfma_f32_16x16x32_bf16 v[2:5], v[154:157], v[194:197], v[2:5]
	v_mfma_f32_16x16x32_bf16 v[54:57], v[150:153], v[174:177], v[54:57]
	v_mfma_f32_16x16x32_bf16 v[50:53], v[158:161], v[174:177], v[50:53]
	v_mfma_f32_16x16x32_bf16 v[38:41], v[150:153], v[182:185], v[38:41]
	v_mfma_f32_16x16x32_bf16 v[34:37], v[158:161], v[182:185], v[34:37]
	v_mfma_f32_16x16x32_bf16 v[22:25], v[150:153], v[190:193], v[22:25]
	v_mfma_f32_16x16x32_bf16 v[18:21], v[158:161], v[190:193], v[18:21]
	v_mfma_f32_16x16x32_bf16 v[6:9], v[150:153], v[200:203], v[6:9]
	v_mfma_f32_16x16x32_bf16 v[2:5], v[158:161], v[200:203], v[2:5]
	s_barrier
	s_setprio 0
	s_cbranch_scc0 .LBB0_1614
	s_mov_b32 m0, s41
	s_nop 0
	buffer_load_dwordx4 v168, s[16:19], s61 offen lds
	s_mov_b32 m0, s33
	s_nop 0
	buffer_load_dwordx4 v170, s[16:19], s61 offen lds
	v_readlane_b32 s2, v251, 45
	v_readlane_b32 s3, v251, 46
	s_and_b64 vcc, exec, s[2:3]
	s_cbranch_vccz .LBB0_1617
	s_barrier
